# P2/P3X->P2b split-phase barrier: arrival with XCD-leader writeback, wait deferred behind the late weight conversions
# speedup vs baseline: 1.0178x; 1.0076x over previous
.LBB0_325:
	s_or_b64 exec, exec, s[12:13]
	s_waitcnt vmcnt(0)
	s_waitcnt lgkmcnt(0)
	s_barrier
	s_and_saveexec_b64 s[10:11], s[92:93]
	s_cbranch_execz .LBB0_377
	v_mov_b32_e32 v2, 0x22000
	ds_read_b32 v4, v2
	s_lshl_b32 s0, s87, 8
	s_add_i32 s0, s0, 0x2b5d018
	v_mov_b32_e32 v2, s0
	v_mov_b32_e32 v3, 1
	global_atomic_add v6, v2, v3, s[88:89] sc0
	s_waitcnt vmcnt(0) lgkmcnt(0)
	v_add_u32_e32 v6, 1, v6
	v_cmp_eq_u32_e32 vcc, v6, v4
	s_cbranch_vccz .Lsb_notlast_p2b
	buffer_wbl2 sc1
	s_waitcnt vmcnt(0)
	v_mov_b32_e32 v2, 0x2b5d01c
	global_atomic_add v2, v3, s[88:89]
.Lsb_notlast_p2b:
.LBB0_377:
	s_or_b64 exec, exec, s[10:11]
	s_waitcnt lgkmcnt(0)
	v_mov_b32_e32 v2, v0
	v_mov_b32_e32 v138, v0
	s_cmp_gt_i32 s2, 7
	s_mov_b64 s[10:11], -1
	v_writelane_b32 v254, s92, 20
	s_barrier
	s_nop 0
	v_writelane_b32 v254, s93, 21
	s_cbranch_scc0 .LBB0_589
	s_cmp_gt_u32 s2, 23
	s_cbranch_scc0 .LBB0_585
	s_load_dwordx2 s[50:51], s[96:97], 0xe8
	s_cmpk_lt_u32 s2, 0x338
	s_cbranch_scc1 .LBB0_381
	s_sub_i32 s3, s90, 24
	s_sub_i32 s28, s2, 24
	s_cbranch_execz .LBB0_382
	s_branch .LBB0_468

.LBB0_468:
	v_readlane_b32 s98, v254, 20
	v_readlane_b32 s99, v254, 21
	s_nop 1
	s_and_saveexec_b64 s[100:101], s[98:99]
	s_cbranch_execz .Lsbw_end_p2b_vt
	v_mov_b32_e32 v2, 0x22004
	ds_read_b32 v4, v2
	v_mov_b32_e32 v2, 0x2b5d01c
	s_mov_b32 s98, 0x100000
	s_waitcnt lgkmcnt(0)
.Lsbw_poll_p2b_vt:
	global_load_dword v3, v2, s[88:89] sc1
	s_waitcnt vmcnt(0)
	v_cmp_ge_u32_e32 vcc, v3, v4
	s_cbranch_vccnz .Lsbw_done_p2b_vt
	s_sleep 1
	s_sub_u32 s98, s98, 1
	s_cmp_lg_u32 s98, 0
	s_cbranch_scc1 .Lsbw_poll_p2b_vt

.Lsbw_end_p2b_vt:
	s_or_b64 exec, exec, s[100:101]
	s_barrier
	s_waitcnt lgkmcnt(0)
	s_add_u32 s4, s50, 0x6e00000
	s_addc_u32 s5, s51, 0
	s_add_u32 s6, s50, 0x4e00000
	s_addc_u32 s7, s51, 0
	s_load_dwordx2 s[14:15], s[96:97], 0xe0
	s_add_u32 s8, s50, 0x1e80000
	s_addc_u32 s9, s51, 0
	s_add_u32 s24, s50, 0x1f00000
	s_addc_u32 s25, s51, 0
	s_waitcnt lgkmcnt(0)
	s_add_u32 s26, s14, 0x2000000
	s_addc_u32 s27, s15, 0
	v_mov_b32_e32 v6, v0
	s_cmpk_lt_i32 s2, 0x118
	s_cselect_b64 s[16:17], -1, 0
	s_cmpk_gt_i32 s2, 0x117
	v_readfirstlane_b32 s1, v6
	s_cbranch_scc1 .LBB0_470
	s_lshl_b32 s10, s28, 6
	s_lshl_b32 s11, s28, 8
	s_bfe_u32 s76, s28, 0x20005
	s_and_b32 s10, s10, 0x2000
	s_and_b32 s11, s11, 0x1f00
	s_and_b32 s0, s28, 0xff
	s_or_b32 s74, s10, s11
	s_lshl_b32 s10, s76, 17
	s_cmpk_lt_u32 s28, 0x100
	s_cselect_b32 s12, s24, s8
	s_cselect_b32 s11, s25, s9
	s_cselect_b32 s13, s7, s5
	s_cselect_b32 s18, s6, s4
	s_cselect_b32 s41, 0, 2
	s_cselect_b32 s19, s15, s27
	s_cselect_b32 s20, s14, s26
	s_add_u32 s78, s12, s10
	s_addc_u32 s79, s11, 0
	s_lshl_b32 s10, s74, 11
	s_lshl_b32 s11, s76, 9
	s_or_b32 s10, s10, s11
	s_add_u32 s12, s18, s10
	s_addc_u32 s13, s13, 0
	s_lshl_b32 s0, s0, 17
	s_add_u32 s10, s20, s0
	s_addc_u32 s11, s19, 0
	s_andn2_b64 vcc, exec, s[16:17]
	s_cbranch_vccz .LBB0_471
	s_branch .LBB0_584

.Lsbw_end_p2b_scan:
	s_or_b64 exec, exec, s[100:101]
	s_barrier
	v_readlane_b32 s0, v254, 9
	v_readlane_b32 s1, v254, 10
	s_mov_b32 s4, s0
	s_ashr_i32 s5, s0, 31
	v_writelane_b32 v254, s0, 9
	v_ashrrev_i32_e32 v139, 31, v138
	s_mov_b32 s14, 0x180000
	v_writelane_b32 v254, s1, 10
	s_lshl_b64 s[0:1], s[4:5], 13
	s_load_dwordx2 s[12:13], s[96:97], 0xa0
	s_load_dwordx2 s[4:5], s[96:97], 0xe8
	v_lshl_add_u64 v[114:115], v[138:139], 4, s[0:1]
	s_lshl_b32 s0, s37, 2
	v_mov_b32_e32 v6, s0
	s_lshl_b32 s0, s37, 16
	s_waitcnt lgkmcnt(0)
	s_add_u32 s1, s4, 0x2119000
	s_addc_u32 s3, s5, 0
	s_add_u32 s10, s1, s0
	s_addc_u32 s11, s3, 0
	s_bitset1_b32 s0, 18
	s_add_u32 s0, s1, s0
	v_lshlrev_b64 v[2:3], 2, v[114:115]
	s_addc_u32 s1, s3, 0
	v_lshl_add_u64 v[66:67], s[0:1], 0, v[2:3]
	s_mov_b32 s3, 0x80000
	v_add_co_u32_e32 v4, vcc, s3, v66
	s_mov_b32 s5, 0x100000
	s_nop 0
	v_addc_co_u32_e32 v5, vcc, 0, v67, vcc
	global_load_dwordx4 v[94:97], v[66:67], off
	global_load_dwordx4 v[110:113], v[4:5], off
	v_add_co_u32_e32 v4, vcc, s5, v66
	s_mov_b32 s4, 0xbfb8aa3b
	s_nop 0
	v_addc_co_u32_e32 v5, vcc, 0, v67, vcc
	global_load_dwordx4 v[122:125], v[4:5], off
	v_add_co_u32_e32 v4, vcc, s14, v66
	s_mov_b64 s[6:7], 0x100000
	s_nop 0
	v_addc_co_u32_e32 v5, vcc, 0, v67, vcc
	global_load_dwordx4 v[126:129], v[4:5], off
	global_load_dword v121, v6, s[12:13] offset:16
	global_load_dword v118, v6, s[12:13]
	global_load_dwordx4 v[98:101], v[66:67], off offset:16
	v_lshl_add_u64 v[6:7], s[10:11], 0, v[2:3]
	v_add_co_u32_e32 v70, vcc, s3, v6
	s_mov_b64 s[0:1], 0x80000
	s_nop 0
	v_addc_co_u32_e32 v71, vcc, 0, v7, vcc
	v_add_co_u32_e32 v78, vcc, s5, v6
	s_mov_b32 s5, 0xb2a5705f
	s_nop 0
	v_addc_co_u32_e32 v79, vcc, 0, v7, vcc
	s_mov_b64 s[8:9], 0x180000
	v_lshl_add_u64 v[72:73], v[6:7], 0, s[6:7]
	v_add_co_u32_e32 v82, vcc, s14, v6
	global_load_dwordx4 v[2:5], v[6:7], off offset:48
	global_load_dwordx4 v[18:21], v[6:7], off offset:32
	global_load_dwordx4 v[34:37], v[6:7], off offset:16
	global_load_dwordx4 v[50:53], v[6:7], off
	v_lshl_add_u64 v[68:69], v[6:7], 0, s[0:1]
	v_lshl_add_u64 v[80:81], v[6:7], 0, s[8:9]
	v_addc_co_u32_e32 v83, vcc, 0, v7, vcc
	global_load_dwordx4 v[62:65], v[70:71], off
	global_load_dwordx4 v[14:17], v[68:69], off offset:48
	global_load_dwordx4 v[30:33], v[68:69], off offset:32
	global_load_dwordx4 v[46:49], v[68:69], off offset:16
	global_load_dwordx4 v[58:61], v[78:79], off
	global_load_dwordx4 v[10:13], v[72:73], off offset:48
	global_load_dwordx4 v[26:29], v[72:73], off offset:32
	global_load_dwordx4 v[42:45], v[72:73], off offset:16
	global_load_dwordx4 v[54:57], v[82:83], off
	global_load_dwordx4 v[6:9], v[80:81], off offset:48
	global_load_dwordx4 v[22:25], v[80:81], off offset:32
	global_load_dwordx4 v[38:41], v[80:81], off offset:16
	global_load_dwordx4 v[74:77], v[66:67], off offset:48
	global_load_dwordx4 v[86:89], v[66:67], off offset:32
	v_lshl_add_u64 v[72:73], v[66:67], 0, s[6:7]
	s_mov_b32 s6, 0x42ce8ed0
	s_mov_b32 s7, 0xc2b17218
	v_lshl_add_u64 v[70:71], v[66:67], 0, s[0:1]
	v_lshl_add_u64 v[116:117], v[66:67], 0, s[8:9]
	global_load_dwordx4 v[78:81], v[70:71], off offset:48
	global_load_dwordx4 v[90:93], v[70:71], off offset:32
	global_load_dwordx4 v[106:109], v[70:71], off offset:16
	global_load_dwordx4 v[66:69], v[72:73], off offset:48
	global_load_dwordx4 v[82:85], v[72:73], off offset:32
	global_load_dwordx4 v[102:105], v[72:73], off offset:16
	s_nop 0
	global_load_dwordx4 v[70:73], v[116:117], off offset:48
	s_mov_b32 s8, 0x3f2aaaab
	s_mov_b32 s9, 0x3f317218
	s_mov_b32 s3, 0x7f800000
	s_mov_b32 s10, 0x33800000
	s_waitcnt vmcnt(0)
	v_pk_add_f32 v[94:95], v[94:95], v[110:111]
	v_pk_add_f32 v[96:97], v[96:97], v[112:113]
	v_pk_add_f32 v[94:95], v[94:95], v[122:123]
	v_pk_add_f32 v[124:125], v[96:97], v[124:125]
	v_pk_add_f32 v[126:127], v[94:95], v[126:127]
	s_nop 0
	v_add_f32_e32 v119, v121, v126
	v_mul_f32_e64 v94, |v119|, s4
	v_fma_f32 v95, |v119|, s4, -v94
	v_rndne_f32_e32 v96, v94
	v_fma_f32 v95, |v119|, s5, v95
	v_sub_f32_e32 v94, v94, v96
	v_add_f32_e32 v94, v94, v95
	v_exp_f32_e32 v120, v94
	v_cvt_i32_f32_e32 v122, v96
	v_cmp_ngt_f32_e64 vcc, |v119|, s6
	global_load_dwordx4 v[94:97], v[116:117], off offset:32
	global_load_dwordx4 v[110:113], v[116:117], off offset:16
	v_pk_add_f32 v[116:117], v[124:125], v[128:129]
	v_ldexp_f32 v120, v120, v122
	v_cndmask_b32_e32 v122, 0, v120, vcc
	v_mov_b32_e32 v120, 0x7f800000
	v_cmp_nlt_f32_e64 vcc, |v119|, s7
	v_min_f32_e32 v124, 0, v119
	v_pk_add_f32 v[74:75], v[74:75], v[78:79]
	v_cndmask_b32_e32 v119, v120, v122, vcc
	v_add_f32_e32 v125, 1.0, v119
	v_add_f32_e32 v122, -1.0, v125
	v_sub_f32_e32 v123, v122, v125
	v_add_f32_e32 v123, 1.0, v123
	v_sub_f32_e32 v122, v119, v122
	v_add_f32_e32 v126, v122, v123
	v_frexp_mant_f32_e32 v128, v125
	v_cvt_f64_f32_e32 v[122:123], v125
	v_frexp_exp_i32_f64_e32 v122, v[122:123]
	v_cmp_gt_f32_e32 vcc, s8, v128
	v_pk_add_f32 v[98:99], v[98:99], v[106:107]
	v_pk_add_f32 v[100:101], v[100:101], v[108:109]
	v_subbrev_co_u32_e32 v122, vcc, 0, v122, vcc
	v_sub_u32_e32 v123, 0, v122
	v_ldexp_f32 v125, v125, v123
	v_ldexp_f32 v123, v126, v123
	v_add_f32_e32 v126, -1.0, v125
	v_add_f32_e32 v130, 1.0, v125
	v_add_f32_e32 v128, 1.0, v126
	v_add_f32_e32 v131, -1.0, v130
	v_sub_f32_e32 v128, v125, v128
	v_sub_f32_e32 v125, v125, v131
	v_add_f32_e32 v128, v123, v128
	v_add_f32_e32 v123, v123, v125
	v_add_f32_e32 v125, v130, v123
	v_rcp_f32_e32 v131, v125
	v_add_f32_e32 v129, v126, v128
	v_sub_f32_e32 v126, v126, v129
	v_add_f32_e32 v126, v128, v126
	v_sub_f32_e32 v128, v130, v125
	v_add_f32_e32 v123, v123, v128
	v_mul_f32_e32 v128, v129, v131
	v_mul_f32_e32 v130, v125, v128
	v_fma_f32 v132, v128, v125, -v130
	v_fmac_f32_e32 v132, v128, v123
	v_add_f32_e32 v133, v130, v132
	v_sub_f32_e32 v134, v129, v133
	v_sub_f32_e32 v129, v129, v134
	v_sub_f32_e32 v130, v133, v130
	v_sub_f32_e32 v129, v129, v133
	v_add_f32_e32 v126, v126, v129
	v_sub_f32_e32 v129, v130, v132
	v_add_f32_e32 v126, v129, v126
	v_add_f32_e32 v129, v134, v126
	v_mul_f32_e32 v130, v131, v129
	v_mul_f32_e32 v132, v125, v130
	v_fma_f32 v125, v130, v125, -v132
	v_fmac_f32_e32 v125, v130, v123
	v_sub_f32_e32 v123, v134, v129
	v_add_f32_e32 v123, v126, v123
	v_add_f32_e32 v126, v132, v125
	v_sub_f32_e32 v133, v129, v126
	v_sub_f32_e32 v129, v129, v133
	v_sub_f32_e32 v132, v126, v132
	v_sub_f32_e32 v126, v129, v126
	v_add_f32_e32 v123, v123, v126
	v_sub_f32_e32 v125, v132, v125
	v_add_f32_e32 v123, v125, v123
	v_add_f32_e32 v123, v133, v123
	v_mul_f32_e32 v123, v131, v123
	v_cvt_f32_i32_e32 v131, v122
	v_add_f32_e32 v125, v128, v130
	v_sub_f32_e32 v126, v125, v128
	v_sub_f32_e32 v126, v130, v126
	v_add_f32_e32 v126, v126, v123
	v_mul_f32_e32 v132, 0x3f317218, v131
	v_add_f32_e32 v128, v125, v126
	v_fma_f32 v133, v131, s9, -v132
	v_mul_f32_e32 v129, v128, v128
	v_mov_b32_e32 v123, 0x3ecc95a3
	v_fmac_f32_e32 v133, 0xb102e308, v131
	v_sub_f32_e32 v125, v128, v125
	v_fmamk_f32 v130, v129, 0x3e9b6dac, v123
	v_sub_f32_e32 v125, v126, v125
	v_add_f32_e32 v126, v132, v133
	v_fmaak_f32 v130, v129, v130, 0x3f2aaada
	v_sub_f32_e32 v131, v126, v132
	v_ldexp_f32 v132, v128, 1
	v_mul_f32_e32 v128, v128, v129
	v_mul_f32_e32 v128, v128, v130
	v_add_f32_e32 v129, v132, v128
	v_sub_f32_e32 v130, v129, v132
	v_ldexp_f32 v125, v125, 1
	v_sub_f32_e32 v128, v128, v130
	v_add_f32_e32 v125, v125, v128
	v_add_f32_e32 v128, v129, v125
	v_sub_f32_e32 v129, v128, v129
	v_sub_f32_e32 v125, v125, v129
	v_add_f32_e32 v129, v126, v128
	v_sub_f32_e32 v130, v129, v126
	v_sub_f32_e32 v132, v129, v130
	v_sub_f32_e32 v131, v133, v131
	v_sub_f32_e32 v126, v126, v132
	v_sub_f32_e32 v128, v128, v130
	v_add_f32_e32 v126, v128, v126
	v_add_f32_e32 v128, v131, v125
	v_sub_f32_e32 v130, v128, v131
	v_add_f32_e32 v126, v128, v126
	v_sub_f32_e32 v132, v128, v130
	v_add_f32_e32 v128, v129, v126
	v_sub_f32_e32 v131, v131, v132
	v_sub_f32_e32 v125, v125, v130
	v_sub_f32_e32 v129, v128, v129
	v_add_f32_e32 v125, v125, v131
	v_sub_f32_e32 v126, v126, v129
	v_add_f32_e32 v125, v125, v126
	v_add_f32_e32 v125, v128, v125
	v_cmp_neq_f32_e32 vcc, s3, v119
	v_pk_add_f32 v[98:99], v[98:99], v[102:103]
	v_pk_add_f32 v[86:87], v[86:87], v[90:91]
	v_cndmask_b32_e32 v125, v120, v125, vcc
	v_cmp_lt_f32_e64 vcc, |v119|, s10
	s_waitcnt vmcnt(0)
	v_pk_add_f32 v[102:103], v[98:99], v[110:111]
	v_pk_add_f32 v[82:83], v[86:87], v[82:83]
	v_cndmask_b32_e32 v119, v125, v119, vcc
	v_add_f32_e32 v125, v121, v127
	v_mul_f32_e64 v126, |v125|, s4
	v_fma_f32 v127, |v125|, s4, -v126
	v_rndne_f32_e32 v128, v126
	v_fma_f32 v127, |v125|, s5, v127
	v_sub_f32_e32 v126, v126, v128
	v_add_f32_e32 v126, v126, v127
	v_exp_f32_e32 v126, v126
	v_cvt_i32_f32_e32 v127, v128
	v_sub_f32_e32 v119, v124, v119
	v_cmp_ngt_f32_e64 vcc, |v125|, s6
	v_min_f32_e32 v128, 0, v125
	v_ldexp_f32 v124, v126, v127
	v_cndmask_b32_e32 v124, 0, v124, vcc
	v_cmp_nlt_f32_e64 vcc, |v125|, s7
	v_add_f32_e32 v102, v121, v102
	v_mul_f32_e64 v98, |v102|, s4
	v_cndmask_b32_e32 v126, v120, v124, vcc
	v_add_f32_e32 v127, 1.0, v126
	v_add_f32_e32 v124, -1.0, v127
	v_sub_f32_e32 v125, v124, v127
	v_add_f32_e32 v125, 1.0, v125
	v_sub_f32_e32 v124, v126, v124
	v_add_f32_e32 v129, v124, v125
	v_frexp_mant_f32_e32 v130, v127
	v_cvt_f64_f32_e32 v[124:125], v127
	v_frexp_exp_i32_f64_e32 v124, v[124:125]
	v_cmp_gt_f32_e32 vcc, s8, v130
	v_fma_f32 v99, |v102|, s4, -v98
	v_rndne_f32_e32 v106, v98
	v_subbrev_co_u32_e32 v124, vcc, 0, v124, vcc
	v_sub_u32_e32 v125, 0, v124
	v_ldexp_f32 v127, v127, v125
	v_ldexp_f32 v125, v129, v125
	v_add_f32_e32 v129, -1.0, v127
	v_add_f32_e32 v132, 1.0, v127
	v_add_f32_e32 v130, 1.0, v129
	v_add_f32_e32 v133, -1.0, v132
	v_sub_f32_e32 v130, v127, v130
	v_sub_f32_e32 v127, v127, v133
	v_add_f32_e32 v130, v125, v130
	v_add_f32_e32 v125, v125, v127
	v_add_f32_e32 v127, v132, v125
	v_rcp_f32_e32 v133, v127
	v_add_f32_e32 v131, v129, v130
	v_sub_f32_e32 v129, v129, v131
	v_add_f32_e32 v129, v130, v129
	v_sub_f32_e32 v130, v132, v127
	v_add_f32_e32 v125, v125, v130
	v_mul_f32_e32 v130, v131, v133
	v_mul_f32_e32 v132, v127, v130
	v_fma_f32 v134, v130, v127, -v132
	v_fmac_f32_e32 v134, v130, v125
	v_add_f32_e32 v135, v132, v134
	v_sub_f32_e32 v136, v131, v135
	v_sub_f32_e32 v131, v131, v136
	v_sub_f32_e32 v132, v135, v132
	v_sub_f32_e32 v131, v131, v135
	v_add_f32_e32 v129, v129, v131
	v_sub_f32_e32 v131, v132, v134
	v_add_f32_e32 v129, v131, v129
	v_add_f32_e32 v131, v136, v129
	v_mul_f32_e32 v132, v133, v131
	v_mul_f32_e32 v134, v127, v132
	v_fma_f32 v127, v132, v127, -v134
	v_fmac_f32_e32 v127, v132, v125
	v_sub_f32_e32 v125, v136, v131
	v_add_f32_e32 v125, v129, v125
	v_add_f32_e32 v129, v134, v127
	v_sub_f32_e32 v135, v131, v129
	v_sub_f32_e32 v131, v131, v135
	v_sub_f32_e32 v134, v129, v134
	v_sub_f32_e32 v129, v131, v129
	v_add_f32_e32 v125, v125, v129
	v_sub_f32_e32 v127, v134, v127
	v_cvt_f32_i32_e32 v124, v124
	v_add_f32_e32 v125, v127, v125
	v_add_f32_e32 v127, v130, v132
	v_add_f32_e32 v125, v135, v125
	v_sub_f32_e32 v129, v127, v130
	v_mul_f32_e32 v125, v133, v125
	v_sub_f32_e32 v129, v132, v129
	v_add_f32_e32 v125, v129, v125
	v_mul_f32_e32 v132, 0x3f317218, v124
	v_add_f32_e32 v129, v127, v125
	v_fma_f32 v133, v124, s9, -v132
	v_mul_f32_e32 v130, v129, v129
	v_fmac_f32_e32 v133, 0xb102e308, v124
	v_sub_f32_e32 v124, v129, v127
	v_fmamk_f32 v131, v130, 0x3e9b6dac, v123
	v_sub_f32_e32 v124, v125, v124
	v_add_f32_e32 v125, v132, v133
	v_fmaak_f32 v131, v130, v131, 0x3f2aaada
	v_sub_f32_e32 v127, v125, v132
	v_ldexp_f32 v132, v129, 1
	v_mul_f32_e32 v129, v129, v130
	v_mul_f32_e32 v129, v129, v131
	v_add_f32_e32 v130, v132, v129
	v_sub_f32_e32 v131, v130, v132
	v_ldexp_f32 v124, v124, 1
	v_sub_f32_e32 v129, v129, v131
	v_add_f32_e32 v124, v124, v129
	v_add_f32_e32 v129, v130, v124
	v_sub_f32_e32 v130, v129, v130
	v_sub_f32_e32 v124, v124, v130
	v_add_f32_e32 v130, v125, v129
	v_sub_f32_e32 v131, v130, v125
	v_sub_f32_e32 v132, v130, v131
	v_sub_f32_e32 v127, v133, v127
	v_sub_f32_e32 v125, v125, v132
	v_sub_f32_e32 v129, v129, v131
	v_add_f32_e32 v125, v129, v125
	v_add_f32_e32 v129, v127, v124
	v_sub_f32_e32 v131, v129, v127
	v_sub_f32_e32 v132, v129, v131
	v_sub_f32_e32 v127, v127, v132
	v_sub_f32_e32 v124, v124, v131
	v_add_f32_e32 v125, v129, v125
	v_add_f32_e32 v124, v124, v127
	v_add_f32_e32 v127, v130, v125
	v_sub_f32_e32 v129, v127, v130
	v_sub_f32_e32 v125, v125, v129
	v_add_f32_e32 v124, v124, v125
	v_add_f32_e32 v124, v127, v124
	v_cmp_neq_f32_e32 vcc, s3, v126
	v_add_f32_e32 v125, v121, v116
	v_mul_f32_e64 v116, |v125|, s4
	v_cndmask_b32_e32 v124, v120, v124, vcc
	v_cmp_lt_f32_e64 vcc, |v126|, s10
	v_rndne_f32_e32 v127, v116
	v_fma_f32 v99, |v102|, s5, v99
	v_cndmask_b32_e32 v124, v124, v126, vcc
	v_fma_f32 v126, |v125|, s4, -v116
	v_fma_f32 v126, |v125|, s5, v126
	v_sub_f32_e32 v116, v116, v127
	v_add_f32_e32 v116, v116, v126
	v_exp_f32_e32 v126, v116
	v_cvt_i32_f32_e32 v127, v127
	v_sub_f32_e32 v116, v128, v124
	v_cmp_ngt_f32_e64 vcc, |v125|, s6
	v_min_f32_e32 v128, 0, v125
	v_ldexp_f32 v124, v126, v127
	v_cndmask_b32_e32 v124, 0, v124, vcc
	v_cmp_nlt_f32_e64 vcc, |v125|, s7
	v_sub_f32_e32 v98, v98, v106
	v_add_f32_e32 v98, v98, v99
	v_cndmask_b32_e32 v126, v120, v124, vcc
	v_add_f32_e32 v127, 1.0, v126
	v_add_f32_e32 v124, -1.0, v127
	v_sub_f32_e32 v125, v124, v127
	v_add_f32_e32 v125, 1.0, v125
	v_sub_f32_e32 v124, v126, v124
	v_add_f32_e32 v129, v124, v125
	v_frexp_mant_f32_e32 v130, v127
	v_cvt_f64_f32_e32 v[124:125], v127
	v_frexp_exp_i32_f64_e32 v124, v[124:125]
	v_cmp_gt_f32_e32 vcc, s8, v130
	v_exp_f32_e32 v107, v98
	v_cvt_i32_f32_e32 v106, v106
	v_subbrev_co_u32_e32 v124, vcc, 0, v124, vcc
	v_sub_u32_e32 v125, 0, v124
	v_ldexp_f32 v127, v127, v125
	v_ldexp_f32 v125, v129, v125
	v_add_f32_e32 v129, -1.0, v127
	v_add_f32_e32 v132, 1.0, v127
	v_add_f32_e32 v130, 1.0, v129
	v_add_f32_e32 v133, -1.0, v132
	v_sub_f32_e32 v130, v127, v130
	v_sub_f32_e32 v127, v127, v133
	v_add_f32_e32 v130, v125, v130
	v_add_f32_e32 v125, v125, v127
	v_add_f32_e32 v127, v132, v125
	v_rcp_f32_e32 v133, v127
	v_add_f32_e32 v131, v129, v130
	v_sub_f32_e32 v129, v129, v131
	v_add_f32_e32 v129, v130, v129
	v_sub_f32_e32 v130, v132, v127
	v_add_f32_e32 v125, v125, v130
	v_mul_f32_e32 v130, v131, v133
	v_mul_f32_e32 v132, v127, v130
	v_fma_f32 v134, v130, v127, -v132
	v_fmac_f32_e32 v134, v130, v125
	v_add_f32_e32 v135, v132, v134
	v_sub_f32_e32 v136, v131, v135
	v_sub_f32_e32 v131, v131, v136
	v_sub_f32_e32 v132, v135, v132
	v_sub_f32_e32 v131, v131, v135
	v_add_f32_e32 v129, v129, v131
	v_sub_f32_e32 v131, v132, v134
	v_add_f32_e32 v129, v131, v129
	v_add_f32_e32 v131, v136, v129
	v_mul_f32_e32 v132, v133, v131
	v_mul_f32_e32 v134, v127, v132
	v_fma_f32 v127, v132, v127, -v134
	v_fmac_f32_e32 v127, v132, v125
	v_sub_f32_e32 v125, v136, v131
	v_add_f32_e32 v125, v129, v125
	v_add_f32_e32 v129, v134, v127
	v_sub_f32_e32 v135, v131, v129
	v_sub_f32_e32 v131, v131, v135
	v_sub_f32_e32 v134, v129, v134
	v_sub_f32_e32 v129, v131, v129
	v_add_f32_e32 v125, v125, v129
	v_sub_f32_e32 v127, v134, v127
	v_cvt_f32_i32_e32 v124, v124
	v_add_f32_e32 v125, v127, v125
	v_add_f32_e32 v127, v130, v132
	v_add_f32_e32 v125, v135, v125
	v_sub_f32_e32 v129, v127, v130
	v_mul_f32_e32 v125, v133, v125
	v_sub_f32_e32 v129, v132, v129
	v_add_f32_e32 v125, v129, v125
	v_mul_f32_e32 v132, 0x3f317218, v124
	v_add_f32_e32 v129, v127, v125
	v_fma_f32 v133, v124, s9, -v132
	v_mul_f32_e32 v130, v129, v129
	v_fmac_f32_e32 v133, 0xb102e308, v124
	v_sub_f32_e32 v124, v129, v127
	v_fmamk_f32 v131, v130, 0x3e9b6dac, v123
	v_sub_f32_e32 v124, v125, v124
	v_add_f32_e32 v125, v132, v133
	v_fmaak_f32 v131, v130, v131, 0x3f2aaada
	v_sub_f32_e32 v127, v125, v132
	v_ldexp_f32 v132, v129, 1
	v_mul_f32_e32 v129, v129, v130
	v_mul_f32_e32 v129, v129, v131
	v_add_f32_e32 v130, v132, v129
	v_sub_f32_e32 v131, v130, v132
	v_ldexp_f32 v124, v124, 1
	v_sub_f32_e32 v129, v129, v131
	v_add_f32_e32 v124, v124, v129
	v_add_f32_e32 v129, v130, v124
	v_sub_f32_e32 v130, v129, v130
	v_sub_f32_e32 v124, v124, v130
	v_add_f32_e32 v130, v125, v129
	v_sub_f32_e32 v131, v130, v125
	v_sub_f32_e32 v132, v130, v131
	v_sub_f32_e32 v127, v133, v127
	v_sub_f32_e32 v125, v125, v132
	v_sub_f32_e32 v129, v129, v131
	v_add_f32_e32 v125, v129, v125
	v_add_f32_e32 v129, v127, v124
	v_sub_f32_e32 v131, v129, v127
	v_sub_f32_e32 v132, v129, v131
	v_sub_f32_e32 v127, v127, v132
	v_sub_f32_e32 v124, v124, v131
	v_add_f32_e32 v125, v129, v125
	v_add_f32_e32 v124, v124, v127
	v_add_f32_e32 v127, v130, v125
	v_sub_f32_e32 v129, v127, v130
	v_sub_f32_e32 v125, v125, v129
	v_add_f32_e32 v124, v124, v125
	v_add_f32_e32 v124, v127, v124
	v_cmp_neq_f32_e32 vcc, s3, v126
	v_add_f32_e32 v125, v121, v117
	v_mul_f32_e64 v117, |v125|, s4
	v_cndmask_b32_e32 v124, v120, v124, vcc
	v_cmp_lt_f32_e64 vcc, |v126|, s10
	v_rndne_f32_e32 v127, v117
	v_pk_add_f32 v[98:99], v[100:101], v[104:105]
	v_cndmask_b32_e32 v124, v124, v126, vcc
	v_fma_f32 v126, |v125|, s4, -v117
	v_fma_f32 v126, |v125|, s5, v126
	v_sub_f32_e32 v117, v117, v127
	v_add_f32_e32 v117, v117, v126
	v_exp_f32_e32 v126, v117
	v_cvt_i32_f32_e32 v127, v127
	v_sub_f32_e32 v117, v128, v124
	v_cmp_ngt_f32_e64 vcc, |v125|, s6
	v_min_f32_e32 v128, 0, v125
	v_ldexp_f32 v124, v126, v127
	v_cndmask_b32_e32 v124, 0, v124, vcc
	v_cmp_nlt_f32_e64 vcc, |v125|, s7
	v_ldexp_f32 v100, v107, v106
	v_min_f32_e32 v104, 0, v102
	v_cndmask_b32_e32 v126, v120, v124, vcc
	v_add_f32_e32 v127, 1.0, v126
	v_add_f32_e32 v124, -1.0, v127
	v_sub_f32_e32 v125, v124, v127
	v_add_f32_e32 v125, 1.0, v125
	v_sub_f32_e32 v124, v126, v124
	v_add_f32_e32 v129, v124, v125
	v_frexp_mant_f32_e32 v130, v127
	v_cvt_f64_f32_e32 v[124:125], v127
	v_frexp_exp_i32_f64_e32 v124, v[124:125]
	v_cmp_gt_f32_e32 vcc, s8, v130
	v_pk_add_f32 v[98:99], v[98:99], v[112:113]
	v_pk_add_f32 v[86:87], v[82:83], v[94:95]
	v_subbrev_co_u32_e32 v124, vcc, 0, v124, vcc
	v_sub_u32_e32 v125, 0, v124
	v_ldexp_f32 v127, v127, v125
	v_ldexp_f32 v125, v129, v125
	v_add_f32_e32 v129, -1.0, v127
	v_add_f32_e32 v132, 1.0, v127
	v_add_f32_e32 v130, 1.0, v129
	v_add_f32_e32 v133, -1.0, v132
	v_sub_f32_e32 v130, v127, v130
	v_sub_f32_e32 v127, v127, v133
	v_add_f32_e32 v130, v125, v130
	v_add_f32_e32 v125, v125, v127
	v_add_f32_e32 v127, v132, v125
	v_rcp_f32_e32 v133, v127
	v_add_f32_e32 v131, v129, v130
	v_sub_f32_e32 v129, v129, v131
	v_add_f32_e32 v129, v130, v129
	v_sub_f32_e32 v130, v132, v127
	v_add_f32_e32 v125, v125, v130
	v_mul_f32_e32 v130, v131, v133
	v_mul_f32_e32 v132, v127, v130
	v_fma_f32 v134, v130, v127, -v132
	v_fmac_f32_e32 v134, v130, v125
	v_add_f32_e32 v135, v132, v134
	v_sub_f32_e32 v136, v131, v135
	v_sub_f32_e32 v131, v131, v136
	v_sub_f32_e32 v132, v135, v132
	v_sub_f32_e32 v131, v131, v135
	v_add_f32_e32 v129, v129, v131
	v_sub_f32_e32 v131, v132, v134
	v_add_f32_e32 v129, v131, v129
	v_add_f32_e32 v131, v136, v129
	v_mul_f32_e32 v132, v133, v131
	v_mul_f32_e32 v134, v127, v132
	v_fma_f32 v127, v132, v127, -v134
	v_fmac_f32_e32 v127, v132, v125
	v_sub_f32_e32 v125, v136, v131
	v_add_f32_e32 v125, v129, v125
	v_add_f32_e32 v129, v134, v127
	v_sub_f32_e32 v135, v131, v129
	v_sub_f32_e32 v131, v131, v135
	v_sub_f32_e32 v134, v129, v134
	v_sub_f32_e32 v129, v131, v129
	v_add_f32_e32 v125, v125, v129
	v_sub_f32_e32 v127, v134, v127
	v_cvt_f32_i32_e32 v124, v124
	v_add_f32_e32 v125, v127, v125
	v_add_f32_e32 v127, v130, v132
	v_add_f32_e32 v125, v135, v125
	v_sub_f32_e32 v129, v127, v130
	v_mul_f32_e32 v125, v133, v125
	v_sub_f32_e32 v129, v132, v129
	v_add_f32_e32 v125, v129, v125
	v_mul_f32_e32 v132, 0x3f317218, v124
	v_add_f32_e32 v129, v127, v125
	v_fma_f32 v133, v124, s9, -v132
	v_mul_f32_e32 v130, v129, v129
	v_fmac_f32_e32 v133, 0xb102e308, v124
	v_sub_f32_e32 v124, v129, v127
	v_fmamk_f32 v131, v130, 0x3e9b6dac, v123
	v_sub_f32_e32 v124, v125, v124
	v_add_f32_e32 v125, v132, v133
	v_fmaak_f32 v131, v130, v131, 0x3f2aaada
	v_sub_f32_e32 v127, v125, v132
	v_ldexp_f32 v132, v129, 1
	v_mul_f32_e32 v129, v129, v130
	v_mul_f32_e32 v129, v129, v131
	v_add_f32_e32 v130, v132, v129
	v_sub_f32_e32 v131, v130, v132
	v_ldexp_f32 v124, v124, 1
	v_sub_f32_e32 v129, v129, v131
	v_add_f32_e32 v124, v124, v129
	v_add_f32_e32 v129, v130, v124
	v_sub_f32_e32 v130, v129, v130
	v_sub_f32_e32 v124, v124, v130
	v_add_f32_e32 v130, v125, v129
	v_sub_f32_e32 v131, v130, v125
	v_sub_f32_e32 v132, v130, v131
	v_sub_f32_e32 v127, v133, v127
	v_sub_f32_e32 v125, v125, v132
	v_sub_f32_e32 v129, v129, v131
	v_add_f32_e32 v125, v129, v125
	v_add_f32_e32 v129, v127, v124
	v_sub_f32_e32 v131, v129, v127
	v_sub_f32_e32 v132, v129, v131
	v_sub_f32_e32 v127, v127, v132
	v_sub_f32_e32 v124, v124, v131
	v_add_f32_e32 v125, v129, v125
	v_add_f32_e32 v124, v124, v127
	v_add_f32_e32 v127, v130, v125
	v_sub_f32_e32 v129, v127, v130
	v_sub_f32_e32 v125, v125, v129
	v_add_f32_e32 v124, v124, v125
	v_add_f32_e32 v124, v127, v124
	v_cmp_neq_f32_e32 vcc, s3, v126
	v_add_f32_e32 v86, v121, v86
	v_mul_f32_e64 v82, |v86|, s4
	v_cndmask_b32_e32 v124, v120, v124, vcc
	v_cmp_lt_f32_e64 vcc, |v126|, s10
	v_fma_f32 v83, |v86|, s4, -v82
	v_rndne_f32_e32 v90, v82
	v_cndmask_b32_e32 v124, v124, v126, vcc
	v_cmp_ngt_f32_e64 vcc, |v102|, s6
	v_fma_f32 v83, |v86|, s5, v83
	v_sub_f32_e32 v82, v82, v90
	v_cndmask_b32_e32 v100, 0, v100, vcc
	v_cmp_nlt_f32_e64 vcc, |v102|, s7
	v_add_f32_e32 v82, v82, v83
	v_exp_f32_e32 v91, v82
	v_cndmask_b32_e32 v102, v120, v100, vcc
	v_add_f32_e32 v105, 1.0, v102
	v_add_f32_e32 v100, -1.0, v105
	v_sub_f32_e32 v101, v100, v105
	v_add_f32_e32 v101, 1.0, v101
	v_sub_f32_e32 v100, v102, v100
	v_add_f32_e32 v106, v100, v101
	v_frexp_mant_f32_e32 v107, v105
	v_cvt_f64_f32_e32 v[100:101], v105
	v_frexp_exp_i32_f64_e32 v100, v[100:101]
	v_cmp_gt_f32_e32 vcc, s8, v107
	v_cvt_i32_f32_e32 v90, v90
	v_pk_add_f32 v[88:89], v[88:89], v[92:93]
	v_subbrev_co_u32_e32 v100, vcc, 0, v100, vcc
	v_sub_u32_e32 v101, 0, v100
	v_ldexp_f32 v105, v105, v101
	v_ldexp_f32 v101, v106, v101
	v_add_f32_e32 v106, -1.0, v105
	v_add_f32_e32 v109, 1.0, v105
	v_add_f32_e32 v107, 1.0, v106
	v_add_f32_e32 v110, -1.0, v109
	v_sub_f32_e32 v107, v105, v107
	v_sub_f32_e32 v105, v105, v110
	v_add_f32_e32 v107, v101, v107
	v_add_f32_e32 v101, v101, v105
	v_add_f32_e32 v105, v109, v101
	v_rcp_f32_e32 v110, v105
	v_add_f32_e32 v108, v106, v107
	v_sub_f32_e32 v106, v106, v108
	v_add_f32_e32 v106, v107, v106
	v_sub_f32_e32 v107, v109, v105
	v_add_f32_e32 v101, v101, v107
	v_mul_f32_e32 v107, v108, v110
	v_mul_f32_e32 v109, v105, v107
	v_fma_f32 v111, v107, v105, -v109
	v_fmac_f32_e32 v111, v107, v101
	v_add_f32_e32 v112, v109, v111
	v_sub_f32_e32 v113, v108, v112
	v_sub_f32_e32 v108, v108, v113
	v_sub_f32_e32 v109, v112, v109
	v_sub_f32_e32 v108, v108, v112
	v_add_f32_e32 v106, v106, v108
	v_sub_f32_e32 v108, v109, v111
	v_add_f32_e32 v106, v108, v106
	v_add_f32_e32 v108, v113, v106
	v_mul_f32_e32 v109, v110, v108
	v_mul_f32_e32 v111, v105, v109
	v_fma_f32 v105, v109, v105, -v111
	v_fmac_f32_e32 v105, v109, v101
	v_sub_f32_e32 v101, v113, v108
	v_add_f32_e32 v101, v106, v101
	v_add_f32_e32 v106, v111, v105
	v_sub_f32_e32 v112, v108, v106
	v_sub_f32_e32 v108, v108, v112
	v_sub_f32_e32 v111, v106, v111
	v_sub_f32_e32 v106, v108, v106
	v_add_f32_e32 v101, v101, v106
	v_sub_f32_e32 v105, v111, v105
	v_cvt_f32_i32_e32 v100, v100
	v_add_f32_e32 v101, v105, v101
	v_add_f32_e32 v105, v107, v109
	v_add_f32_e32 v101, v112, v101
	v_sub_f32_e32 v106, v105, v107
	v_mul_f32_e32 v101, v110, v101
	v_sub_f32_e32 v106, v109, v106
	v_add_f32_e32 v101, v106, v101
	v_mul_f32_e32 v109, 0x3f317218, v100
	v_add_f32_e32 v106, v105, v101
	v_fma_f32 v110, v100, s9, -v109
	v_mul_f32_e32 v107, v106, v106
	v_fmac_f32_e32 v110, 0xb102e308, v100
	v_sub_f32_e32 v100, v106, v105
	v_fmamk_f32 v108, v107, 0x3e9b6dac, v123
	v_sub_f32_e32 v100, v101, v100
	v_add_f32_e32 v101, v109, v110
	v_fmaak_f32 v108, v107, v108, 0x3f2aaada
	v_sub_f32_e32 v105, v101, v109
	v_ldexp_f32 v109, v106, 1
	v_mul_f32_e32 v106, v106, v107
	v_mul_f32_e32 v106, v106, v108
	v_add_f32_e32 v107, v109, v106
	v_sub_f32_e32 v108, v107, v109
	v_ldexp_f32 v100, v100, 1
	v_sub_f32_e32 v106, v106, v108
	v_add_f32_e32 v100, v100, v106
	v_add_f32_e32 v106, v107, v100
	v_sub_f32_e32 v107, v106, v107
	v_sub_f32_e32 v100, v100, v107
	v_add_f32_e32 v107, v101, v106
	v_sub_f32_e32 v108, v107, v101
	v_sub_f32_e32 v109, v107, v108
	v_sub_f32_e32 v105, v110, v105
	v_sub_f32_e32 v101, v101, v109
	v_sub_f32_e32 v106, v106, v108
	v_add_f32_e32 v101, v106, v101
	v_add_f32_e32 v106, v105, v100
	v_sub_f32_e32 v108, v106, v105
	v_sub_f32_e32 v109, v106, v108
	v_sub_f32_e32 v105, v105, v109
	v_sub_f32_e32 v100, v100, v108
	v_add_f32_e32 v101, v106, v101
	v_add_f32_e32 v100, v100, v105
	v_add_f32_e32 v105, v107, v101
	v_sub_f32_e32 v106, v105, v107
	v_sub_f32_e32 v101, v101, v106
	v_add_f32_e32 v100, v100, v101
	v_add_f32_e32 v100, v105, v100
	v_cmp_neq_f32_e32 vcc, s3, v102
	v_add_f32_e32 v101, v121, v103
	v_pk_add_f32 v[82:83], v[88:89], v[84:85]
	v_cndmask_b32_e32 v100, v120, v100, vcc
	v_cmp_lt_f32_e64 vcc, |v102|, s10
	v_ldexp_f32 v84, v91, v90
	v_min_f32_e32 v88, 0, v86
	v_cndmask_b32_e32 v100, v100, v102, vcc
	v_mul_f32_e64 v102, |v101|, s4
	v_fma_f32 v103, |v101|, s4, -v102
	v_rndne_f32_e32 v105, v102
	v_fma_f32 v103, |v101|, s5, v103
	v_sub_f32_e32 v102, v102, v105
	v_add_f32_e32 v102, v102, v103
	v_exp_f32_e32 v102, v102
	v_cvt_i32_f32_e32 v103, v105
	v_cmp_ngt_f32_e64 vcc, |v101|, s6
	v_sub_f32_e32 v100, v104, v100
	v_min_f32_e32 v104, 0, v101
	v_ldexp_f32 v102, v102, v103
	v_cndmask_b32_e32 v102, 0, v102, vcc
	v_cmp_nlt_f32_e64 vcc, |v101|, s7
	v_pk_add_f32 v[82:83], v[82:83], v[96:97]
	v_pk_add_f32 v[66:67], v[74:75], v[66:67]
	v_cndmask_b32_e32 v101, v120, v102, vcc
	v_add_f32_e32 v105, 1.0, v101
	v_add_f32_e32 v102, -1.0, v105
	v_sub_f32_e32 v103, v102, v105
	v_add_f32_e32 v103, 1.0, v103
	v_sub_f32_e32 v102, v101, v102
	v_add_f32_e32 v106, v102, v103
	v_frexp_mant_f32_e32 v107, v105
	v_cvt_f64_f32_e32 v[102:103], v105
	v_frexp_exp_i32_f64_e32 v102, v[102:103]
	v_cmp_gt_f32_e32 vcc, s8, v107
	v_pk_add_f32 v[70:71], v[66:67], v[70:71]
	v_pk_add_f32 v[76:77], v[76:77], v[80:81]
	v_subbrev_co_u32_e32 v102, vcc, 0, v102, vcc
	v_sub_u32_e32 v103, 0, v102
	v_ldexp_f32 v105, v105, v103
	v_ldexp_f32 v103, v106, v103
	v_add_f32_e32 v106, -1.0, v105
	v_add_f32_e32 v109, 1.0, v105
	v_add_f32_e32 v107, 1.0, v106
	v_add_f32_e32 v110, -1.0, v109
	v_sub_f32_e32 v107, v105, v107
	v_sub_f32_e32 v105, v105, v110
	v_add_f32_e32 v107, v103, v107
	v_add_f32_e32 v103, v103, v105
	v_add_f32_e32 v105, v109, v103
	v_rcp_f32_e32 v110, v105
	v_add_f32_e32 v108, v106, v107
	v_sub_f32_e32 v106, v106, v108
	v_add_f32_e32 v106, v107, v106
	v_sub_f32_e32 v107, v109, v105
	v_add_f32_e32 v103, v103, v107
	v_mul_f32_e32 v107, v108, v110
	v_mul_f32_e32 v109, v105, v107
	v_fma_f32 v111, v107, v105, -v109
	v_fmac_f32_e32 v111, v107, v103
	v_add_f32_e32 v112, v109, v111
	v_sub_f32_e32 v113, v108, v112
	v_sub_f32_e32 v108, v108, v113
	v_sub_f32_e32 v109, v112, v109
	v_sub_f32_e32 v108, v108, v112
	v_add_f32_e32 v106, v106, v108
	v_sub_f32_e32 v108, v109, v111
	v_add_f32_e32 v106, v108, v106
	v_add_f32_e32 v108, v113, v106
	v_mul_f32_e32 v109, v110, v108
	v_mul_f32_e32 v111, v105, v109
	v_fma_f32 v105, v109, v105, -v111
	v_fmac_f32_e32 v105, v109, v103
	v_sub_f32_e32 v103, v113, v108
	v_add_f32_e32 v103, v106, v103
	v_add_f32_e32 v106, v111, v105
	v_sub_f32_e32 v112, v108, v106
	v_sub_f32_e32 v108, v108, v112
	v_sub_f32_e32 v111, v106, v111
	v_sub_f32_e32 v106, v108, v106
	v_add_f32_e32 v103, v103, v106
	v_sub_f32_e32 v105, v111, v105
	v_cvt_f32_i32_e32 v102, v102
	v_add_f32_e32 v103, v105, v103
	v_add_f32_e32 v105, v107, v109
	v_add_f32_e32 v103, v112, v103
	v_sub_f32_e32 v106, v105, v107
	v_mul_f32_e32 v103, v110, v103
	v_sub_f32_e32 v106, v109, v106
	v_add_f32_e32 v103, v106, v103
	v_mul_f32_e32 v109, 0x3f317218, v102
	v_add_f32_e32 v106, v105, v103
	v_fma_f32 v110, v102, s9, -v109
	v_mul_f32_e32 v107, v106, v106
	v_fmac_f32_e32 v110, 0xb102e308, v102
	v_sub_f32_e32 v102, v106, v105
	v_fmamk_f32 v108, v107, 0x3e9b6dac, v123
	v_sub_f32_e32 v102, v103, v102
	v_add_f32_e32 v103, v109, v110
	v_fmaak_f32 v108, v107, v108, 0x3f2aaada
	v_sub_f32_e32 v105, v103, v109
	v_ldexp_f32 v109, v106, 1
	v_mul_f32_e32 v106, v106, v107
	v_mul_f32_e32 v106, v106, v108
	v_add_f32_e32 v107, v109, v106
	v_sub_f32_e32 v108, v107, v109
	v_ldexp_f32 v102, v102, 1
	v_sub_f32_e32 v106, v106, v108
	v_add_f32_e32 v102, v102, v106
	v_add_f32_e32 v106, v107, v102
	v_sub_f32_e32 v107, v106, v107
	v_sub_f32_e32 v102, v102, v107
	v_add_f32_e32 v107, v103, v106
	v_sub_f32_e32 v108, v107, v103
	v_sub_f32_e32 v109, v107, v108
	v_sub_f32_e32 v105, v110, v105
	v_sub_f32_e32 v103, v103, v109
	v_sub_f32_e32 v106, v106, v108
	v_add_f32_e32 v103, v106, v103
	v_add_f32_e32 v106, v105, v102
	v_sub_f32_e32 v108, v106, v105
	v_sub_f32_e32 v109, v106, v108
	v_sub_f32_e32 v105, v105, v109
	v_sub_f32_e32 v102, v102, v108
	v_add_f32_e32 v103, v106, v103
	v_add_f32_e32 v102, v102, v105
	v_add_f32_e32 v105, v107, v103
	v_sub_f32_e32 v106, v105, v107
	v_sub_f32_e32 v103, v103, v106
	v_add_f32_e32 v102, v102, v103
	v_add_f32_e32 v102, v105, v102
	v_cmp_neq_f32_e32 vcc, s3, v101
	v_add_f32_e32 v70, v121, v70
	v_mul_f32_e64 v66, |v70|, s4
	v_cndmask_b32_e32 v102, v120, v102, vcc
	v_cmp_lt_f32_e64 vcc, |v101|, s10
	v_fma_f32 v67, |v70|, s4, -v66
	v_rndne_f32_e32 v74, v66
	v_cndmask_b32_e32 v101, v102, v101, vcc
	v_add_f32_e32 v102, v121, v98
	v_mul_f32_e64 v98, |v102|, s4
	v_fma_f32 v103, |v102|, s4, -v98
	v_rndne_f32_e32 v105, v98
	v_fma_f32 v103, |v102|, s5, v103
	v_sub_f32_e32 v98, v98, v105
	v_add_f32_e32 v98, v98, v103
	v_exp_f32_e32 v103, v98
	v_cvt_i32_f32_e32 v105, v105
	v_cmp_ngt_f32_e64 vcc, |v102|, s6
	v_sub_f32_e32 v98, v104, v101
	v_min_f32_e32 v101, 0, v102
	v_ldexp_f32 v103, v103, v105
	v_cndmask_b32_e32 v103, 0, v103, vcc
	v_cmp_nlt_f32_e64 vcc, |v102|, s7
	v_fma_f32 v67, |v70|, s5, v67
	v_sub_f32_e32 v66, v66, v74
	v_cndmask_b32_e32 v104, v120, v103, vcc
	v_add_f32_e32 v105, 1.0, v104
	v_add_f32_e32 v102, -1.0, v105
	v_sub_f32_e32 v103, v102, v105
	v_add_f32_e32 v103, 1.0, v103
	v_sub_f32_e32 v102, v104, v102
	v_add_f32_e32 v106, v102, v103
	v_frexp_mant_f32_e32 v107, v105
	v_cvt_f64_f32_e32 v[102:103], v105
	v_frexp_exp_i32_f64_e32 v102, v[102:103]
	v_cmp_gt_f32_e32 vcc, s8, v107
	v_add_f32_e32 v66, v66, v67
	v_exp_f32_e32 v75, v66
	v_subbrev_co_u32_e32 v102, vcc, 0, v102, vcc
	v_sub_u32_e32 v103, 0, v102
	v_ldexp_f32 v105, v105, v103
	v_ldexp_f32 v103, v106, v103
	v_add_f32_e32 v106, -1.0, v105
	v_add_f32_e32 v109, 1.0, v105
	v_add_f32_e32 v107, 1.0, v106
	v_add_f32_e32 v110, -1.0, v109
	v_sub_f32_e32 v107, v105, v107
	v_sub_f32_e32 v105, v105, v110
	v_add_f32_e32 v107, v103, v107
	v_add_f32_e32 v103, v103, v105
	v_add_f32_e32 v105, v109, v103
	v_rcp_f32_e32 v110, v105
	v_add_f32_e32 v108, v106, v107
	v_sub_f32_e32 v106, v106, v108
	v_add_f32_e32 v106, v107, v106
	v_sub_f32_e32 v107, v109, v105
	v_add_f32_e32 v103, v103, v107
	v_mul_f32_e32 v107, v108, v110
	v_mul_f32_e32 v109, v105, v107
	v_fma_f32 v111, v107, v105, -v109
	v_fmac_f32_e32 v111, v107, v103
	v_add_f32_e32 v112, v109, v111
	v_sub_f32_e32 v113, v108, v112
	v_sub_f32_e32 v108, v108, v113
	v_sub_f32_e32 v109, v112, v109
	v_sub_f32_e32 v108, v108, v112
	v_add_f32_e32 v106, v106, v108
	v_sub_f32_e32 v108, v109, v111
	v_add_f32_e32 v106, v108, v106
	v_add_f32_e32 v108, v113, v106
	v_mul_f32_e32 v109, v110, v108
	v_mul_f32_e32 v111, v105, v109
	v_fma_f32 v105, v109, v105, -v111
	v_fmac_f32_e32 v105, v109, v103
	v_sub_f32_e32 v103, v113, v108
	v_add_f32_e32 v103, v106, v103
	v_add_f32_e32 v106, v111, v105
	v_sub_f32_e32 v112, v108, v106
	v_sub_f32_e32 v108, v108, v112
	v_sub_f32_e32 v111, v106, v111
	v_sub_f32_e32 v106, v108, v106
	v_add_f32_e32 v103, v103, v106
	v_sub_f32_e32 v105, v111, v105
	v_cvt_f32_i32_e32 v102, v102
	v_add_f32_e32 v103, v105, v103
	v_add_f32_e32 v105, v107, v109
	v_add_f32_e32 v103, v112, v103
	v_sub_f32_e32 v106, v105, v107
	v_mul_f32_e32 v103, v110, v103
	v_sub_f32_e32 v106, v109, v106
	v_add_f32_e32 v103, v106, v103
	v_mul_f32_e32 v109, 0x3f317218, v102
	v_add_f32_e32 v106, v105, v103
	v_fma_f32 v110, v102, s9, -v109
	v_mul_f32_e32 v107, v106, v106
	v_fmac_f32_e32 v110, 0xb102e308, v102
	v_sub_f32_e32 v102, v106, v105
	v_fmamk_f32 v108, v107, 0x3e9b6dac, v123
	v_sub_f32_e32 v102, v103, v102
	v_add_f32_e32 v103, v109, v110
	v_fmaak_f32 v108, v107, v108, 0x3f2aaada
	v_sub_f32_e32 v105, v103, v109
	v_ldexp_f32 v109, v106, 1
	v_mul_f32_e32 v106, v106, v107
	v_mul_f32_e32 v106, v106, v108
	v_add_f32_e32 v107, v109, v106
	v_sub_f32_e32 v108, v107, v109
	v_ldexp_f32 v102, v102, 1
	v_sub_f32_e32 v106, v106, v108
	v_add_f32_e32 v102, v102, v106
	v_add_f32_e32 v106, v107, v102
	v_sub_f32_e32 v107, v106, v107
	v_sub_f32_e32 v102, v102, v107
	v_add_f32_e32 v107, v103, v106
	v_sub_f32_e32 v108, v107, v103
	v_sub_f32_e32 v109, v107, v108
	v_sub_f32_e32 v105, v110, v105
	v_sub_f32_e32 v103, v103, v109
	v_sub_f32_e32 v106, v106, v108
	v_add_f32_e32 v103, v106, v103
	v_add_f32_e32 v106, v105, v102
	v_sub_f32_e32 v108, v106, v105
	v_sub_f32_e32 v109, v106, v108
	v_sub_f32_e32 v105, v105, v109
	v_sub_f32_e32 v102, v102, v108
	v_add_f32_e32 v103, v106, v103
	v_add_f32_e32 v102, v102, v105
	v_add_f32_e32 v105, v107, v103
	v_sub_f32_e32 v106, v105, v107
	v_sub_f32_e32 v103, v103, v106
	v_add_f32_e32 v102, v102, v103
	v_add_f32_e32 v102, v105, v102
	v_cmp_neq_f32_e32 vcc, s3, v104
	v_add_f32_e32 v103, v121, v99
	v_mul_f32_e64 v99, |v103|, s4
	v_cndmask_b32_e32 v102, v120, v102, vcc
	v_cmp_lt_f32_e64 vcc, |v104|, s10
	v_rndne_f32_e32 v105, v99
	v_cvt_i32_f32_e32 v74, v74
	v_cndmask_b32_e32 v102, v102, v104, vcc
	v_fma_f32 v104, |v103|, s4, -v99
	v_fma_f32 v104, |v103|, s5, v104
	v_sub_f32_e32 v99, v99, v105
	v_add_f32_e32 v99, v99, v104
	v_exp_f32_e32 v104, v99
	v_cvt_i32_f32_e32 v105, v105
	v_sub_f32_e32 v99, v101, v102
	v_cmp_ngt_f32_e64 vcc, |v103|, s6
	v_min_f32_e32 v101, 0, v103
	v_ldexp_f32 v102, v104, v105
	v_cndmask_b32_e32 v102, 0, v102, vcc
	v_cmp_nlt_f32_e64 vcc, |v103|, s7
	v_pk_add_f32 v[66:67], v[76:77], v[68:69]
	v_ldexp_f32 v68, v75, v74
	v_cndmask_b32_e32 v104, v120, v102, vcc
	v_add_f32_e32 v105, 1.0, v104
	v_add_f32_e32 v102, -1.0, v105
	v_sub_f32_e32 v103, v102, v105
	v_add_f32_e32 v103, 1.0, v103
	v_sub_f32_e32 v102, v104, v102
	v_add_f32_e32 v106, v102, v103
	v_frexp_mant_f32_e32 v107, v105
	v_cvt_f64_f32_e32 v[102:103], v105
	v_frexp_exp_i32_f64_e32 v102, v[102:103]
	v_cmp_gt_f32_e32 vcc, s8, v107
	v_pk_add_f32 v[66:67], v[66:67], v[72:73]
	v_min_f32_e32 v72, 0, v70
	v_subbrev_co_u32_e32 v102, vcc, 0, v102, vcc
	v_sub_u32_e32 v103, 0, v102
	v_ldexp_f32 v105, v105, v103
	v_ldexp_f32 v103, v106, v103
	v_add_f32_e32 v106, -1.0, v105
	v_add_f32_e32 v109, 1.0, v105
	v_add_f32_e32 v107, 1.0, v106
	v_add_f32_e32 v110, -1.0, v109
	v_sub_f32_e32 v107, v105, v107
	v_sub_f32_e32 v105, v105, v110
	v_add_f32_e32 v107, v103, v107
	v_add_f32_e32 v103, v103, v105
	v_add_f32_e32 v105, v109, v103
	v_rcp_f32_e32 v110, v105
	v_add_f32_e32 v108, v106, v107
	v_sub_f32_e32 v106, v106, v108
	v_add_f32_e32 v106, v107, v106
	v_sub_f32_e32 v107, v109, v105
	v_add_f32_e32 v103, v103, v107
	v_mul_f32_e32 v107, v108, v110
	v_mul_f32_e32 v109, v105, v107
	v_fma_f32 v111, v107, v105, -v109
	v_fmac_f32_e32 v111, v107, v103
	v_add_f32_e32 v112, v109, v111
	v_sub_f32_e32 v113, v108, v112
	v_sub_f32_e32 v108, v108, v113
	v_sub_f32_e32 v109, v112, v109
	v_sub_f32_e32 v108, v108, v112
	v_add_f32_e32 v106, v106, v108
	v_sub_f32_e32 v108, v109, v111
	v_add_f32_e32 v106, v108, v106
	v_add_f32_e32 v108, v113, v106
	v_mul_f32_e32 v109, v110, v108
	v_mul_f32_e32 v111, v105, v109
	v_fma_f32 v105, v109, v105, -v111
	v_fmac_f32_e32 v105, v109, v103
	v_sub_f32_e32 v103, v113, v108
	v_add_f32_e32 v103, v106, v103
	v_add_f32_e32 v106, v111, v105
	v_sub_f32_e32 v112, v108, v106
	v_sub_f32_e32 v108, v108, v112
	v_sub_f32_e32 v111, v106, v111
	v_sub_f32_e32 v106, v108, v106
	v_add_f32_e32 v103, v103, v106
	v_sub_f32_e32 v105, v111, v105
	v_cvt_f32_i32_e32 v102, v102
	v_add_f32_e32 v103, v105, v103
	v_add_f32_e32 v105, v107, v109
	v_add_f32_e32 v103, v112, v103
	v_sub_f32_e32 v106, v105, v107
	v_mul_f32_e32 v103, v110, v103
	v_sub_f32_e32 v106, v109, v106
	v_add_f32_e32 v103, v106, v103
	v_mul_f32_e32 v109, 0x3f317218, v102
	v_add_f32_e32 v106, v105, v103
	v_fma_f32 v110, v102, s9, -v109
	v_mul_f32_e32 v107, v106, v106
	v_fmac_f32_e32 v110, 0xb102e308, v102
	v_sub_f32_e32 v102, v106, v105
	v_fmamk_f32 v108, v107, 0x3e9b6dac, v123
	v_sub_f32_e32 v102, v103, v102
	v_add_f32_e32 v103, v109, v110
	v_fmaak_f32 v108, v107, v108, 0x3f2aaada
	v_sub_f32_e32 v105, v103, v109
	v_ldexp_f32 v109, v106, 1
	v_mul_f32_e32 v106, v106, v107
	v_mul_f32_e32 v106, v106, v108
	v_add_f32_e32 v107, v109, v106
	v_sub_f32_e32 v108, v107, v109
	v_ldexp_f32 v102, v102, 1
	v_sub_f32_e32 v106, v106, v108
	v_add_f32_e32 v102, v102, v106
	v_add_f32_e32 v106, v107, v102
	v_sub_f32_e32 v107, v106, v107
	v_sub_f32_e32 v102, v102, v107
	v_add_f32_e32 v107, v103, v106
	v_sub_f32_e32 v108, v107, v103
	v_sub_f32_e32 v109, v107, v108
	v_sub_f32_e32 v105, v110, v105
	v_sub_f32_e32 v103, v103, v109
	v_sub_f32_e32 v106, v106, v108
	v_add_f32_e32 v103, v106, v103
	v_add_f32_e32 v106, v105, v102
	v_sub_f32_e32 v108, v106, v105
	v_sub_f32_e32 v109, v106, v108
	v_sub_f32_e32 v105, v105, v109
	v_sub_f32_e32 v102, v102, v108
	v_add_f32_e32 v103, v106, v103
	v_add_f32_e32 v102, v102, v105
	v_add_f32_e32 v105, v107, v103
	v_sub_f32_e32 v106, v105, v107
	v_sub_f32_e32 v103, v103, v106
	v_add_f32_e32 v102, v102, v103
	v_add_f32_e32 v102, v105, v102
	v_cmp_neq_f32_e32 vcc, s3, v104
	v_add_f32_e32 v67, v121, v67
	v_mov_b32_e32 v122, 0x3f2aaada
	v_cndmask_b32_e32 v102, v120, v102, vcc
	v_cmp_lt_f32_e64 vcc, |v104|, s10
	v_add_f32_e32 v119, 0, v119
	v_add_f32_e32 v116, v119, v116
	v_cndmask_b32_e32 v102, v102, v104, vcc
	v_cmp_ngt_f32_e64 vcc, |v86|, s6
	v_add_f32_e32 v117, v116, v117
	v_sub_f32_e32 v124, v128, v124
	v_cndmask_b32_e32 v84, 0, v84, vcc
	v_cmp_nlt_f32_e64 vcc, |v86|, s7
	v_add_f32_e32 v124, v117, v124
	v_add_f32_e32 v100, v124, v100
	v_cndmask_b32_e32 v86, v120, v84, vcc
	v_add_f32_e32 v89, 1.0, v86
	v_add_f32_e32 v84, -1.0, v89
	v_sub_f32_e32 v85, v84, v89
	v_add_f32_e32 v85, 1.0, v85
	v_sub_f32_e32 v84, v86, v84
	v_add_f32_e32 v90, v84, v85
	v_frexp_mant_f32_e32 v91, v89
	v_cvt_f64_f32_e32 v[84:85], v89
	v_frexp_exp_i32_f64_e32 v84, v[84:85]
	v_cmp_gt_f32_e32 vcc, s8, v91
	v_add_f32_e32 v98, v100, v98
	v_add_f32_e32 v99, v98, v99
	v_subbrev_co_u32_e32 v84, vcc, 0, v84, vcc
	v_sub_u32_e32 v85, 0, v84
	v_ldexp_f32 v89, v89, v85
	v_ldexp_f32 v85, v90, v85
	v_add_f32_e32 v90, -1.0, v89
	v_add_f32_e32 v93, 1.0, v89
	v_add_f32_e32 v91, 1.0, v90
	v_add_f32_e32 v94, -1.0, v93
	v_sub_f32_e32 v91, v89, v91
	v_sub_f32_e32 v89, v89, v94
	v_add_f32_e32 v91, v85, v91
	v_add_f32_e32 v85, v85, v89
	v_add_f32_e32 v89, v93, v85
	v_rcp_f32_e32 v94, v89
	v_add_f32_e32 v92, v90, v91
	v_sub_f32_e32 v90, v90, v92
	v_add_f32_e32 v90, v91, v90
	v_sub_f32_e32 v91, v93, v89
	v_add_f32_e32 v85, v85, v91
	v_mul_f32_e32 v91, v92, v94
	v_mul_f32_e32 v93, v89, v91
	v_fma_f32 v95, v91, v89, -v93
	v_fmac_f32_e32 v95, v91, v85
	v_add_f32_e32 v96, v93, v95
	v_sub_f32_e32 v97, v92, v96
	v_sub_f32_e32 v92, v92, v97
	v_sub_f32_e32 v93, v96, v93
	v_sub_f32_e32 v92, v92, v96
	v_add_f32_e32 v90, v90, v92
	v_sub_f32_e32 v92, v93, v95
	v_add_f32_e32 v90, v92, v90
	v_add_f32_e32 v92, v97, v90
	v_mul_f32_e32 v93, v94, v92
	v_mul_f32_e32 v95, v89, v93
	v_fma_f32 v89, v93, v89, -v95
	v_fmac_f32_e32 v89, v93, v85
	v_sub_f32_e32 v85, v97, v92
	v_add_f32_e32 v85, v90, v85
	v_add_f32_e32 v90, v95, v89
	v_sub_f32_e32 v96, v92, v90
	v_sub_f32_e32 v92, v92, v96
	v_sub_f32_e32 v95, v90, v95
	v_sub_f32_e32 v90, v92, v90
	v_add_f32_e32 v85, v85, v90
	v_sub_f32_e32 v89, v95, v89
	v_cvt_f32_i32_e32 v84, v84
	v_add_f32_e32 v85, v89, v85
	v_add_f32_e32 v89, v91, v93
	v_add_f32_e32 v85, v96, v85
	v_sub_f32_e32 v90, v89, v91
	v_mul_f32_e32 v85, v94, v85
	v_sub_f32_e32 v90, v93, v90
	v_add_f32_e32 v85, v90, v85
	v_mul_f32_e32 v93, 0x3f317218, v84
	v_add_f32_e32 v90, v89, v85
	v_fma_f32 v94, v84, s9, -v93
	v_mul_f32_e32 v91, v90, v90
	v_fmac_f32_e32 v94, 0xb102e308, v84
	v_sub_f32_e32 v84, v90, v89
	v_fmamk_f32 v92, v91, 0x3e9b6dac, v123
	v_sub_f32_e32 v84, v85, v84
	v_add_f32_e32 v85, v93, v94
	v_fmaak_f32 v92, v91, v92, 0x3f2aaada
	v_sub_f32_e32 v89, v85, v93
	v_ldexp_f32 v93, v90, 1
	v_mul_f32_e32 v90, v90, v91
	v_mul_f32_e32 v90, v90, v92
	v_add_f32_e32 v91, v93, v90
	v_sub_f32_e32 v92, v91, v93
	v_ldexp_f32 v84, v84, 1
	v_sub_f32_e32 v90, v90, v92
	v_add_f32_e32 v84, v84, v90
	v_add_f32_e32 v90, v91, v84
	v_sub_f32_e32 v91, v90, v91
	v_sub_f32_e32 v84, v84, v91
	v_add_f32_e32 v91, v85, v90
	v_sub_f32_e32 v92, v91, v85
	v_sub_f32_e32 v93, v91, v92
	v_sub_f32_e32 v89, v94, v89
	v_sub_f32_e32 v85, v85, v93
	v_sub_f32_e32 v90, v90, v92
	v_add_f32_e32 v85, v90, v85
	v_add_f32_e32 v90, v89, v84
	v_sub_f32_e32 v92, v90, v89
	v_sub_f32_e32 v93, v90, v92
	v_sub_f32_e32 v89, v89, v93
	v_sub_f32_e32 v84, v84, v92
	v_add_f32_e32 v85, v90, v85
	v_add_f32_e32 v84, v84, v89
	v_add_f32_e32 v89, v91, v85
	v_sub_f32_e32 v90, v89, v91
	v_sub_f32_e32 v85, v85, v90
	v_add_f32_e32 v84, v84, v85
	v_add_f32_e32 v84, v89, v84
	v_cmp_neq_f32_e32 vcc, s3, v86
	v_add_f32_e32 v85, v121, v87
	v_sub_f32_e32 v101, v101, v102
	v_cndmask_b32_e32 v84, v120, v84, vcc
	v_cmp_lt_f32_e64 vcc, |v86|, s10
	v_add_f32_e32 v101, v99, v101
	s_nop 0
	v_cndmask_b32_e32 v84, v84, v86, vcc
	v_mul_f32_e64 v86, |v85|, s4
	v_fma_f32 v87, |v85|, s4, -v86
	v_rndne_f32_e32 v89, v86
	v_fma_f32 v87, |v85|, s5, v87
	v_sub_f32_e32 v86, v86, v89
	v_add_f32_e32 v86, v86, v87
	v_exp_f32_e32 v86, v86
	v_cvt_i32_f32_e32 v87, v89
	v_cmp_ngt_f32_e64 vcc, |v85|, s6
	v_sub_f32_e32 v84, v88, v84
	v_min_f32_e32 v88, 0, v85
	v_ldexp_f32 v86, v86, v87
	v_cndmask_b32_e32 v86, 0, v86, vcc
	v_cmp_nlt_f32_e64 vcc, |v85|, s7
	v_add_f32_e32 v84, v101, v84
	s_nop 0
	v_cndmask_b32_e32 v85, v120, v86, vcc
	v_add_f32_e32 v89, 1.0, v85
	v_add_f32_e32 v86, -1.0, v89
	v_sub_f32_e32 v87, v86, v89
	v_add_f32_e32 v87, 1.0, v87
	v_sub_f32_e32 v86, v85, v86
	v_add_f32_e32 v90, v86, v87
	v_frexp_mant_f32_e32 v91, v89
	v_cvt_f64_f32_e32 v[86:87], v89
	v_frexp_exp_i32_f64_e32 v86, v[86:87]
	v_cmp_gt_f32_e32 vcc, s8, v91
	s_nop 1
	v_subbrev_co_u32_e32 v86, vcc, 0, v86, vcc
	v_sub_u32_e32 v87, 0, v86
	v_ldexp_f32 v89, v89, v87
	v_ldexp_f32 v87, v90, v87
	v_add_f32_e32 v90, -1.0, v89
	v_add_f32_e32 v93, 1.0, v89
	v_add_f32_e32 v91, 1.0, v90
	v_add_f32_e32 v94, -1.0, v93
	v_sub_f32_e32 v91, v89, v91
	v_sub_f32_e32 v89, v89, v94
	v_add_f32_e32 v91, v87, v91
	v_add_f32_e32 v87, v87, v89
	v_add_f32_e32 v89, v93, v87
	v_rcp_f32_e32 v94, v89
	v_add_f32_e32 v92, v90, v91
	v_sub_f32_e32 v90, v90, v92
	v_add_f32_e32 v90, v91, v90
	v_sub_f32_e32 v91, v93, v89
	v_add_f32_e32 v87, v87, v91
	v_mul_f32_e32 v91, v92, v94
	v_mul_f32_e32 v93, v89, v91
	v_fma_f32 v95, v91, v89, -v93
	v_fmac_f32_e32 v95, v91, v87
	v_add_f32_e32 v96, v93, v95
	v_sub_f32_e32 v97, v92, v96
	v_sub_f32_e32 v92, v92, v97
	v_sub_f32_e32 v93, v96, v93
	v_sub_f32_e32 v92, v92, v96
	v_add_f32_e32 v90, v90, v92
	v_sub_f32_e32 v92, v93, v95
	v_add_f32_e32 v90, v92, v90
	v_add_f32_e32 v92, v97, v90
	v_mul_f32_e32 v93, v94, v92
	v_mul_f32_e32 v95, v89, v93
	v_fma_f32 v89, v93, v89, -v95
	v_fmac_f32_e32 v89, v93, v87
	v_sub_f32_e32 v87, v97, v92
	v_add_f32_e32 v87, v90, v87
	v_add_f32_e32 v90, v95, v89
	v_sub_f32_e32 v96, v92, v90
	v_sub_f32_e32 v92, v92, v96
	v_sub_f32_e32 v95, v90, v95
	v_sub_f32_e32 v90, v92, v90
	v_add_f32_e32 v87, v87, v90
	v_sub_f32_e32 v89, v95, v89
	v_cvt_f32_i32_e32 v86, v86
	v_add_f32_e32 v87, v89, v87
	v_add_f32_e32 v89, v91, v93
	v_add_f32_e32 v87, v96, v87
	v_sub_f32_e32 v90, v89, v91
	v_mul_f32_e32 v87, v94, v87
	v_sub_f32_e32 v90, v93, v90
	v_add_f32_e32 v87, v90, v87
	v_mul_f32_e32 v93, 0x3f317218, v86
	v_add_f32_e32 v90, v89, v87
	v_fma_f32 v94, v86, s9, -v93
	v_mul_f32_e32 v91, v90, v90
	v_fmac_f32_e32 v94, 0xb102e308, v86
	v_sub_f32_e32 v86, v90, v89
	v_fmamk_f32 v92, v91, 0x3e9b6dac, v123
	v_sub_f32_e32 v86, v87, v86
	v_add_f32_e32 v87, v93, v94
	v_fmaak_f32 v92, v91, v92, 0x3f2aaada
	v_sub_f32_e32 v89, v87, v93
	v_ldexp_f32 v93, v90, 1
	v_mul_f32_e32 v90, v90, v91
	v_mul_f32_e32 v90, v90, v92
	v_add_f32_e32 v91, v93, v90
	v_sub_f32_e32 v92, v91, v93
	v_ldexp_f32 v86, v86, 1
	v_sub_f32_e32 v90, v90, v92
	v_add_f32_e32 v86, v86, v90
	v_add_f32_e32 v90, v91, v86
	v_sub_f32_e32 v91, v90, v91
	v_sub_f32_e32 v86, v86, v91
	v_add_f32_e32 v91, v87, v90
	v_sub_f32_e32 v92, v91, v87
	v_sub_f32_e32 v93, v91, v92
	v_sub_f32_e32 v89, v94, v89
	v_sub_f32_e32 v87, v87, v93
	v_sub_f32_e32 v90, v90, v92
	v_add_f32_e32 v87, v90, v87
	v_add_f32_e32 v90, v89, v86
	v_sub_f32_e32 v92, v90, v89
	v_sub_f32_e32 v93, v90, v92
	v_sub_f32_e32 v89, v89, v93
	v_sub_f32_e32 v86, v86, v92
	v_add_f32_e32 v87, v90, v87
	v_add_f32_e32 v86, v86, v89
	v_add_f32_e32 v89, v91, v87
	v_sub_f32_e32 v90, v89, v91
	v_sub_f32_e32 v87, v87, v90
	v_add_f32_e32 v86, v86, v87
	v_add_f32_e32 v86, v89, v86
	v_cmp_neq_f32_e32 vcc, s3, v85
	s_nop 1
	v_cndmask_b32_e32 v86, v120, v86, vcc
	v_cmp_lt_f32_e64 vcc, |v85|, s10
	s_nop 1
	v_cndmask_b32_e32 v85, v86, v85, vcc
	v_add_f32_e32 v86, v121, v82
	v_mul_f32_e64 v82, |v86|, s4
	v_fma_f32 v87, |v86|, s4, -v82
	v_rndne_f32_e32 v89, v82
	v_fma_f32 v87, |v86|, s5, v87
	v_sub_f32_e32 v82, v82, v89
	v_add_f32_e32 v82, v82, v87
	v_exp_f32_e32 v87, v82
	v_cvt_i32_f32_e32 v89, v89
	v_cmp_ngt_f32_e64 vcc, |v86|, s6
	v_sub_f32_e32 v82, v88, v85
	v_min_f32_e32 v85, 0, v86
	v_ldexp_f32 v87, v87, v89
	v_cndmask_b32_e32 v87, 0, v87, vcc
	v_cmp_nlt_f32_e64 vcc, |v86|, s7
	v_add_f32_e32 v82, v84, v82
	s_nop 0
	v_cndmask_b32_e32 v88, v120, v87, vcc
	v_add_f32_e32 v89, 1.0, v88
	v_add_f32_e32 v86, -1.0, v89
	v_sub_f32_e32 v87, v86, v89
	v_add_f32_e32 v87, 1.0, v87
	v_sub_f32_e32 v86, v88, v86
	v_add_f32_e32 v90, v86, v87
	v_frexp_mant_f32_e32 v91, v89
	v_cvt_f64_f32_e32 v[86:87], v89
	v_frexp_exp_i32_f64_e32 v86, v[86:87]
	v_cmp_gt_f32_e32 vcc, s8, v91
	s_nop 1
	v_subbrev_co_u32_e32 v86, vcc, 0, v86, vcc
	v_sub_u32_e32 v87, 0, v86
	v_ldexp_f32 v89, v89, v87
	v_ldexp_f32 v87, v90, v87
	v_add_f32_e32 v90, -1.0, v89
	v_add_f32_e32 v93, 1.0, v89
	v_add_f32_e32 v91, 1.0, v90
	v_add_f32_e32 v94, -1.0, v93
	v_sub_f32_e32 v91, v89, v91
	v_sub_f32_e32 v89, v89, v94
	v_add_f32_e32 v91, v87, v91
	v_add_f32_e32 v87, v87, v89
	v_add_f32_e32 v89, v93, v87
	v_rcp_f32_e32 v94, v89
	v_add_f32_e32 v92, v90, v91
	v_sub_f32_e32 v90, v90, v92
	v_add_f32_e32 v90, v91, v90
	v_sub_f32_e32 v91, v93, v89
	v_add_f32_e32 v87, v87, v91
	v_mul_f32_e32 v91, v92, v94
	v_mul_f32_e32 v93, v89, v91
	v_fma_f32 v95, v91, v89, -v93
	v_fmac_f32_e32 v95, v91, v87
	v_add_f32_e32 v96, v93, v95
	v_sub_f32_e32 v97, v92, v96
	v_sub_f32_e32 v92, v92, v97
	v_sub_f32_e32 v93, v96, v93
	v_sub_f32_e32 v92, v92, v96
	v_add_f32_e32 v90, v90, v92
	v_sub_f32_e32 v92, v93, v95
	v_add_f32_e32 v90, v92, v90
	v_add_f32_e32 v92, v97, v90
	v_mul_f32_e32 v93, v94, v92
	v_mul_f32_e32 v95, v89, v93
	v_fma_f32 v89, v93, v89, -v95
	v_fmac_f32_e32 v89, v93, v87
	v_sub_f32_e32 v87, v97, v92
	v_add_f32_e32 v87, v90, v87
	v_add_f32_e32 v90, v95, v89
	v_sub_f32_e32 v96, v92, v90
	v_sub_f32_e32 v92, v92, v96
	v_sub_f32_e32 v95, v90, v95
	v_sub_f32_e32 v90, v92, v90
	v_add_f32_e32 v87, v87, v90
	v_sub_f32_e32 v89, v95, v89
	v_cvt_f32_i32_e32 v86, v86
	v_add_f32_e32 v87, v89, v87
	v_add_f32_e32 v89, v91, v93
	v_add_f32_e32 v87, v96, v87
	v_sub_f32_e32 v90, v89, v91
	v_mul_f32_e32 v87, v94, v87
	v_sub_f32_e32 v90, v93, v90
	v_add_f32_e32 v87, v90, v87
	v_mul_f32_e32 v93, 0x3f317218, v86
	v_add_f32_e32 v90, v89, v87
	v_fma_f32 v94, v86, s9, -v93
	v_mul_f32_e32 v91, v90, v90
	v_fmac_f32_e32 v94, 0xb102e308, v86
	v_sub_f32_e32 v86, v90, v89
	v_fmamk_f32 v92, v91, 0x3e9b6dac, v123
	v_sub_f32_e32 v86, v87, v86
	v_add_f32_e32 v87, v93, v94
	v_fmaak_f32 v92, v91, v92, 0x3f2aaada
	v_sub_f32_e32 v89, v87, v93
	v_ldexp_f32 v93, v90, 1
	v_mul_f32_e32 v90, v90, v91
	v_mul_f32_e32 v90, v90, v92
	v_add_f32_e32 v91, v93, v90
	v_sub_f32_e32 v92, v91, v93
	v_ldexp_f32 v86, v86, 1
	v_sub_f32_e32 v90, v90, v92
	v_add_f32_e32 v86, v86, v90
	v_add_f32_e32 v90, v91, v86
	v_sub_f32_e32 v91, v90, v91
	v_sub_f32_e32 v86, v86, v91
	v_add_f32_e32 v91, v87, v90
	v_sub_f32_e32 v92, v91, v87
	v_sub_f32_e32 v93, v91, v92
	v_sub_f32_e32 v89, v94, v89
	v_sub_f32_e32 v87, v87, v93
	v_sub_f32_e32 v90, v90, v92
	v_add_f32_e32 v87, v90, v87
	v_add_f32_e32 v90, v89, v86
	v_sub_f32_e32 v92, v90, v89
	v_sub_f32_e32 v93, v90, v92
	v_sub_f32_e32 v89, v89, v93
	v_sub_f32_e32 v86, v86, v92
	v_add_f32_e32 v87, v90, v87
	v_add_f32_e32 v86, v86, v89
	v_add_f32_e32 v89, v91, v87
	v_sub_f32_e32 v90, v89, v91
	v_sub_f32_e32 v87, v87, v90
	v_add_f32_e32 v86, v86, v87
	v_add_f32_e32 v86, v89, v86
	v_cmp_neq_f32_e32 vcc, s3, v88
	v_add_f32_e32 v87, v121, v83
	v_mul_f32_e64 v83, |v87|, s4
	v_cndmask_b32_e32 v86, v120, v86, vcc
	v_cmp_lt_f32_e64 vcc, |v88|, s10
	v_rndne_f32_e32 v89, v83
	s_nop 0
	v_cndmask_b32_e32 v86, v86, v88, vcc
	v_fma_f32 v88, |v87|, s4, -v83
	v_fma_f32 v88, |v87|, s5, v88
	v_sub_f32_e32 v83, v83, v89
	v_add_f32_e32 v83, v83, v88
	v_exp_f32_e32 v88, v83
	v_cvt_i32_f32_e32 v89, v89
	v_sub_f32_e32 v83, v85, v86
	v_cmp_ngt_f32_e64 vcc, |v87|, s6
	v_min_f32_e32 v85, 0, v87
	v_ldexp_f32 v86, v88, v89
	v_cndmask_b32_e32 v86, 0, v86, vcc
	v_cmp_nlt_f32_e64 vcc, |v87|, s7
	v_add_f32_e32 v83, v82, v83
	s_nop 0
	v_cndmask_b32_e32 v88, v120, v86, vcc
	v_add_f32_e32 v89, 1.0, v88
	v_add_f32_e32 v86, -1.0, v89
	v_sub_f32_e32 v87, v86, v89
	v_add_f32_e32 v87, 1.0, v87
	v_sub_f32_e32 v86, v88, v86
	v_add_f32_e32 v90, v86, v87
	v_frexp_mant_f32_e32 v91, v89
	v_cvt_f64_f32_e32 v[86:87], v89
	v_frexp_exp_i32_f64_e32 v86, v[86:87]
	v_cmp_gt_f32_e32 vcc, s8, v91
	s_nop 1
	v_subbrev_co_u32_e32 v86, vcc, 0, v86, vcc
	v_sub_u32_e32 v87, 0, v86
	v_ldexp_f32 v89, v89, v87
	v_ldexp_f32 v87, v90, v87
	v_add_f32_e32 v90, -1.0, v89
	v_add_f32_e32 v93, 1.0, v89
	v_add_f32_e32 v91, 1.0, v90
	v_add_f32_e32 v94, -1.0, v93
	v_sub_f32_e32 v91, v89, v91
	v_sub_f32_e32 v89, v89, v94
	v_add_f32_e32 v91, v87, v91
	v_add_f32_e32 v87, v87, v89
	v_add_f32_e32 v89, v93, v87
	v_rcp_f32_e32 v94, v89
	v_add_f32_e32 v92, v90, v91
	v_sub_f32_e32 v90, v90, v92
	v_add_f32_e32 v90, v91, v90
	v_sub_f32_e32 v91, v93, v89
	v_add_f32_e32 v87, v87, v91
	v_mul_f32_e32 v91, v92, v94
	v_mul_f32_e32 v93, v89, v91
	v_fma_f32 v95, v91, v89, -v93
	v_fmac_f32_e32 v95, v91, v87
	v_add_f32_e32 v96, v93, v95
	v_sub_f32_e32 v97, v92, v96
	v_sub_f32_e32 v92, v92, v97
	v_sub_f32_e32 v93, v96, v93
	v_sub_f32_e32 v92, v92, v96
	v_add_f32_e32 v90, v90, v92
	v_sub_f32_e32 v92, v93, v95
	v_add_f32_e32 v90, v92, v90
	v_add_f32_e32 v92, v97, v90
	v_mul_f32_e32 v93, v94, v92
	v_mul_f32_e32 v95, v89, v93
	v_fma_f32 v89, v93, v89, -v95
	v_fmac_f32_e32 v89, v93, v87
	v_sub_f32_e32 v87, v97, v92
	v_add_f32_e32 v87, v90, v87
	v_add_f32_e32 v90, v95, v89
	v_sub_f32_e32 v96, v92, v90
	v_sub_f32_e32 v92, v92, v96
	v_sub_f32_e32 v95, v90, v95
	v_sub_f32_e32 v90, v92, v90
	v_add_f32_e32 v87, v87, v90
	v_sub_f32_e32 v89, v95, v89
	v_cvt_f32_i32_e32 v86, v86
	v_add_f32_e32 v87, v89, v87
	v_add_f32_e32 v89, v91, v93
	v_add_f32_e32 v87, v96, v87
	v_sub_f32_e32 v90, v89, v91
	v_mul_f32_e32 v87, v94, v87
	v_sub_f32_e32 v90, v93, v90
	v_add_f32_e32 v87, v90, v87
	v_mul_f32_e32 v93, 0x3f317218, v86
	v_add_f32_e32 v90, v89, v87
	v_fma_f32 v94, v86, s9, -v93
	v_mul_f32_e32 v91, v90, v90
	v_fmac_f32_e32 v94, 0xb102e308, v86
	v_sub_f32_e32 v86, v90, v89
	v_fmamk_f32 v92, v91, 0x3e9b6dac, v123
	v_sub_f32_e32 v86, v87, v86
	v_add_f32_e32 v87, v93, v94
	v_fmaak_f32 v92, v91, v92, 0x3f2aaada
	v_sub_f32_e32 v89, v87, v93
	v_ldexp_f32 v93, v90, 1
	v_mul_f32_e32 v90, v90, v91
	v_mul_f32_e32 v90, v90, v92
	v_add_f32_e32 v91, v93, v90
	v_sub_f32_e32 v92, v91, v93
	v_ldexp_f32 v86, v86, 1
	v_sub_f32_e32 v90, v90, v92
	v_add_f32_e32 v86, v86, v90
	v_add_f32_e32 v90, v91, v86
	v_sub_f32_e32 v91, v90, v91
	v_sub_f32_e32 v86, v86, v91
	v_add_f32_e32 v91, v87, v90
	v_sub_f32_e32 v92, v91, v87
	v_sub_f32_e32 v93, v91, v92
	v_sub_f32_e32 v89, v94, v89
	v_sub_f32_e32 v87, v87, v93
	v_sub_f32_e32 v90, v90, v92
	v_add_f32_e32 v87, v90, v87
	v_add_f32_e32 v90, v89, v86
	v_sub_f32_e32 v92, v90, v89
	v_sub_f32_e32 v93, v90, v92
	v_sub_f32_e32 v89, v89, v93
	v_sub_f32_e32 v86, v86, v92
	v_add_f32_e32 v87, v90, v87
	v_add_f32_e32 v86, v86, v89
	v_add_f32_e32 v89, v91, v87
	v_sub_f32_e32 v90, v89, v91
	v_sub_f32_e32 v87, v87, v90
	v_add_f32_e32 v86, v86, v87
	v_add_f32_e32 v86, v89, v86
	v_cmp_neq_f32_e32 vcc, s3, v88
	s_nop 1
	v_cndmask_b32_e32 v86, v120, v86, vcc
	v_cmp_lt_f32_e64 vcc, |v88|, s10
	s_nop 1
	v_cndmask_b32_e32 v86, v86, v88, vcc
	v_cmp_ngt_f32_e64 vcc, |v70|, s6
	v_sub_f32_e32 v85, v85, v86
	v_add_f32_e32 v85, v83, v85
	v_cndmask_b32_e32 v68, 0, v68, vcc
	v_cmp_nlt_f32_e64 vcc, |v70|, s7
	s_nop 1
	v_cndmask_b32_e32 v70, v120, v68, vcc
	v_add_f32_e32 v73, 1.0, v70
	v_add_f32_e32 v68, -1.0, v73
	v_sub_f32_e32 v69, v68, v73
	v_add_f32_e32 v69, 1.0, v69
	v_sub_f32_e32 v68, v70, v68
	v_add_f32_e32 v74, v68, v69
	v_frexp_mant_f32_e32 v75, v73
	v_cvt_f64_f32_e32 v[68:69], v73
	v_frexp_exp_i32_f64_e32 v68, v[68:69]
	v_cmp_gt_f32_e32 vcc, s8, v75
	s_nop 1
	v_subbrev_co_u32_e32 v68, vcc, 0, v68, vcc
	v_sub_u32_e32 v69, 0, v68
	v_ldexp_f32 v73, v73, v69
	v_ldexp_f32 v69, v74, v69
	v_add_f32_e32 v74, -1.0, v73
	v_add_f32_e32 v77, 1.0, v73
	v_add_f32_e32 v75, 1.0, v74
	v_add_f32_e32 v78, -1.0, v77
	v_sub_f32_e32 v75, v73, v75
	v_sub_f32_e32 v73, v73, v78
	v_add_f32_e32 v75, v69, v75
	v_add_f32_e32 v69, v69, v73
	v_add_f32_e32 v73, v77, v69
	v_rcp_f32_e32 v78, v73
	v_add_f32_e32 v76, v74, v75
	v_sub_f32_e32 v74, v74, v76
	v_add_f32_e32 v74, v75, v74
	v_sub_f32_e32 v75, v77, v73
	v_add_f32_e32 v69, v69, v75
	v_mul_f32_e32 v75, v76, v78
	v_mul_f32_e32 v77, v73, v75
	v_fma_f32 v79, v75, v73, -v77
	v_fmac_f32_e32 v79, v75, v69
	v_add_f32_e32 v80, v77, v79
	v_sub_f32_e32 v81, v76, v80
	v_sub_f32_e32 v76, v76, v81
	v_sub_f32_e32 v77, v80, v77
	v_sub_f32_e32 v76, v76, v80
	v_add_f32_e32 v74, v74, v76
	v_sub_f32_e32 v76, v77, v79
	v_add_f32_e32 v74, v76, v74
	v_add_f32_e32 v76, v81, v74
	v_mul_f32_e32 v77, v78, v76
	v_mul_f32_e32 v79, v73, v77
	v_fma_f32 v73, v77, v73, -v79
	v_fmac_f32_e32 v73, v77, v69
	v_sub_f32_e32 v69, v81, v76
	v_add_f32_e32 v69, v74, v69
	v_add_f32_e32 v74, v79, v73
	v_sub_f32_e32 v80, v76, v74
	v_sub_f32_e32 v76, v76, v80
	v_sub_f32_e32 v79, v74, v79
	v_sub_f32_e32 v74, v76, v74
	v_add_f32_e32 v69, v69, v74
	v_sub_f32_e32 v73, v79, v73
	v_cvt_f32_i32_e32 v68, v68
	v_add_f32_e32 v69, v73, v69
	v_add_f32_e32 v73, v75, v77
	v_add_f32_e32 v69, v80, v69
	v_sub_f32_e32 v74, v73, v75
	v_mul_f32_e32 v69, v78, v69
	v_sub_f32_e32 v74, v77, v74
	v_add_f32_e32 v69, v74, v69
	v_mul_f32_e32 v77, 0x3f317218, v68
	v_add_f32_e32 v74, v73, v69
	v_fma_f32 v78, v68, s9, -v77
	v_mul_f32_e32 v75, v74, v74
	v_fmac_f32_e32 v78, 0xb102e308, v68
	v_sub_f32_e32 v68, v74, v73
	v_fmamk_f32 v76, v75, 0x3e9b6dac, v123
	v_sub_f32_e32 v68, v69, v68
	v_add_f32_e32 v69, v77, v78
	v_fmaak_f32 v76, v75, v76, 0x3f2aaada
	v_sub_f32_e32 v73, v69, v77
	v_ldexp_f32 v77, v74, 1
	v_mul_f32_e32 v74, v74, v75
	v_mul_f32_e32 v74, v74, v76
	v_add_f32_e32 v75, v77, v74
	v_sub_f32_e32 v76, v75, v77
	v_ldexp_f32 v68, v68, 1
	v_sub_f32_e32 v74, v74, v76
	v_add_f32_e32 v68, v68, v74
	v_add_f32_e32 v74, v75, v68
	v_sub_f32_e32 v75, v74, v75
	v_sub_f32_e32 v68, v68, v75
	v_add_f32_e32 v75, v69, v74
	v_sub_f32_e32 v76, v75, v69
	v_sub_f32_e32 v77, v75, v76
	v_sub_f32_e32 v73, v78, v73
	v_sub_f32_e32 v69, v69, v77
	v_sub_f32_e32 v74, v74, v76
	v_add_f32_e32 v69, v74, v69
	v_add_f32_e32 v74, v73, v68
	v_sub_f32_e32 v76, v74, v73
	v_sub_f32_e32 v77, v74, v76
	v_sub_f32_e32 v73, v73, v77
	v_sub_f32_e32 v68, v68, v76
	v_add_f32_e32 v69, v74, v69
	v_add_f32_e32 v68, v68, v73
	v_add_f32_e32 v73, v75, v69
	v_sub_f32_e32 v74, v73, v75
	v_sub_f32_e32 v69, v69, v74
	v_add_f32_e32 v68, v68, v69
	v_add_f32_e32 v68, v73, v68
	v_cmp_neq_f32_e32 vcc, s3, v70
	v_add_f32_e32 v69, v121, v71
	s_nop 0
	v_cndmask_b32_e32 v68, v120, v68, vcc
	v_cmp_lt_f32_e64 vcc, |v70|, s10
	s_nop 1
	v_cndmask_b32_e32 v68, v68, v70, vcc
	v_mul_f32_e64 v70, |v69|, s4
	v_fma_f32 v71, |v69|, s4, -v70
	v_rndne_f32_e32 v73, v70
	v_fma_f32 v71, |v69|, s5, v71
	v_sub_f32_e32 v70, v70, v73
	v_add_f32_e32 v70, v70, v71
	v_exp_f32_e32 v70, v70
	v_cvt_i32_f32_e32 v71, v73
	v_cmp_ngt_f32_e64 vcc, |v69|, s6
	v_sub_f32_e32 v68, v72, v68
	v_min_f32_e32 v72, 0, v69
	v_ldexp_f32 v70, v70, v71
	v_cndmask_b32_e32 v70, 0, v70, vcc
	v_cmp_nlt_f32_e64 vcc, |v69|, s7
	v_add_f32_e32 v68, v85, v68
	s_nop 0
	v_cndmask_b32_e32 v69, v120, v70, vcc
	v_add_f32_e32 v73, 1.0, v69
	v_add_f32_e32 v70, -1.0, v73
	v_sub_f32_e32 v71, v70, v73
	v_add_f32_e32 v71, 1.0, v71
	v_sub_f32_e32 v70, v69, v70
	v_add_f32_e32 v74, v70, v71
	v_frexp_mant_f32_e32 v75, v73
	v_cvt_f64_f32_e32 v[70:71], v73
	v_frexp_exp_i32_f64_e32 v70, v[70:71]
	v_cmp_gt_f32_e32 vcc, s8, v75
	s_nop 1
	v_subbrev_co_u32_e32 v70, vcc, 0, v70, vcc
	v_sub_u32_e32 v71, 0, v70
	v_ldexp_f32 v73, v73, v71
	v_ldexp_f32 v71, v74, v71
	v_add_f32_e32 v74, -1.0, v73
	v_add_f32_e32 v77, 1.0, v73
	v_add_f32_e32 v75, 1.0, v74
	v_add_f32_e32 v78, -1.0, v77
	v_sub_f32_e32 v75, v73, v75
	v_sub_f32_e32 v73, v73, v78
	v_add_f32_e32 v75, v71, v75
	v_add_f32_e32 v71, v71, v73
	v_add_f32_e32 v73, v77, v71
	v_rcp_f32_e32 v78, v73
	v_add_f32_e32 v76, v74, v75
	v_sub_f32_e32 v74, v74, v76
	v_add_f32_e32 v74, v75, v74
	v_sub_f32_e32 v75, v77, v73
	v_add_f32_e32 v71, v71, v75
	v_mul_f32_e32 v75, v76, v78
	v_mul_f32_e32 v77, v73, v75
	v_fma_f32 v79, v75, v73, -v77
	v_fmac_f32_e32 v79, v75, v71
	v_add_f32_e32 v80, v77, v79
	v_sub_f32_e32 v81, v76, v80
	v_sub_f32_e32 v76, v76, v81
	v_sub_f32_e32 v77, v80, v77
	v_sub_f32_e32 v76, v76, v80
	v_add_f32_e32 v74, v74, v76
	v_sub_f32_e32 v76, v77, v79
	v_add_f32_e32 v74, v76, v74
	v_add_f32_e32 v76, v81, v74
	v_mul_f32_e32 v77, v78, v76
	v_mul_f32_e32 v79, v73, v77
	v_fma_f32 v73, v77, v73, -v79
	v_fmac_f32_e32 v73, v77, v71
	v_sub_f32_e32 v71, v81, v76
	v_add_f32_e32 v71, v74, v71
	v_add_f32_e32 v74, v79, v73
	v_sub_f32_e32 v80, v76, v74
	v_sub_f32_e32 v76, v76, v80
	v_sub_f32_e32 v79, v74, v79
	v_sub_f32_e32 v74, v76, v74
	v_add_f32_e32 v71, v71, v74
	v_sub_f32_e32 v73, v79, v73
	v_cvt_f32_i32_e32 v70, v70
	v_add_f32_e32 v71, v73, v71
	v_add_f32_e32 v73, v75, v77
	v_add_f32_e32 v71, v80, v71
	v_sub_f32_e32 v74, v73, v75
	v_mul_f32_e32 v71, v78, v71
	v_sub_f32_e32 v74, v77, v74
	v_add_f32_e32 v71, v74, v71
	v_mul_f32_e32 v77, 0x3f317218, v70
	v_add_f32_e32 v74, v73, v71
	v_fma_f32 v78, v70, s9, -v77
	v_mul_f32_e32 v75, v74, v74
	v_fmac_f32_e32 v78, 0xb102e308, v70
	v_sub_f32_e32 v70, v74, v73
	v_fmamk_f32 v76, v75, 0x3e9b6dac, v123
	v_sub_f32_e32 v70, v71, v70
	v_add_f32_e32 v71, v77, v78
	v_fmaak_f32 v76, v75, v76, 0x3f2aaada
	v_sub_f32_e32 v73, v71, v77
	v_ldexp_f32 v77, v74, 1
	v_mul_f32_e32 v74, v74, v75
	v_mul_f32_e32 v74, v74, v76
	v_add_f32_e32 v75, v77, v74
	v_sub_f32_e32 v76, v75, v77
	v_ldexp_f32 v70, v70, 1
	v_sub_f32_e32 v74, v74, v76
	v_add_f32_e32 v70, v70, v74
	v_add_f32_e32 v74, v75, v70
	v_sub_f32_e32 v75, v74, v75
	v_sub_f32_e32 v70, v70, v75
	v_add_f32_e32 v75, v71, v74
	v_sub_f32_e32 v76, v75, v71
	v_sub_f32_e32 v77, v75, v76
	v_sub_f32_e32 v73, v78, v73
	v_sub_f32_e32 v71, v71, v77
	v_sub_f32_e32 v74, v74, v76
	v_add_f32_e32 v71, v74, v71
	v_add_f32_e32 v74, v73, v70
	v_sub_f32_e32 v76, v74, v73
	v_sub_f32_e32 v77, v74, v76
	v_sub_f32_e32 v73, v73, v77
	v_sub_f32_e32 v70, v70, v76
	v_add_f32_e32 v71, v74, v71
	v_add_f32_e32 v70, v70, v73
	v_add_f32_e32 v73, v75, v71
	v_sub_f32_e32 v74, v73, v75
	v_sub_f32_e32 v71, v71, v74
	v_add_f32_e32 v70, v70, v71
	v_add_f32_e32 v70, v73, v70
	v_cmp_neq_f32_e32 vcc, s3, v69
	s_nop 1
	v_cndmask_b32_e32 v70, v120, v70, vcc
	v_cmp_lt_f32_e64 vcc, |v69|, s10
	s_nop 1
	v_cndmask_b32_e32 v69, v70, v69, vcc
	v_add_f32_e32 v70, v121, v66
	v_mul_f32_e64 v66, |v70|, s4
	v_fma_f32 v71, |v70|, s4, -v66
	v_rndne_f32_e32 v73, v66
	v_fma_f32 v71, |v70|, s5, v71
	v_sub_f32_e32 v66, v66, v73
	v_add_f32_e32 v66, v66, v71
	v_exp_f32_e32 v71, v66
	v_cvt_i32_f32_e32 v73, v73
	v_cmp_ngt_f32_e64 vcc, |v70|, s6
	v_sub_f32_e32 v66, v72, v69
	v_min_f32_e32 v69, 0, v70
	v_ldexp_f32 v71, v71, v73
	v_cndmask_b32_e32 v71, 0, v71, vcc
	v_cmp_nlt_f32_e64 vcc, |v70|, s7
	v_add_f32_e32 v66, v68, v66
	s_nop 0
	v_cndmask_b32_e32 v72, v120, v71, vcc
	v_add_f32_e32 v73, 1.0, v72
	v_add_f32_e32 v70, -1.0, v73
	v_sub_f32_e32 v71, v70, v73
	v_add_f32_e32 v71, 1.0, v71
	v_sub_f32_e32 v70, v72, v70
	v_add_f32_e32 v74, v70, v71
	v_frexp_mant_f32_e32 v75, v73
	v_cvt_f64_f32_e32 v[70:71], v73
	v_frexp_exp_i32_f64_e32 v70, v[70:71]
	v_cmp_gt_f32_e32 vcc, s8, v75
	s_nop 1
	v_subbrev_co_u32_e32 v70, vcc, 0, v70, vcc
	v_sub_u32_e32 v71, 0, v70
	v_ldexp_f32 v73, v73, v71
	v_ldexp_f32 v71, v74, v71
	v_add_f32_e32 v74, -1.0, v73
	v_add_f32_e32 v77, 1.0, v73
	v_add_f32_e32 v75, 1.0, v74
	v_add_f32_e32 v78, -1.0, v77
	v_sub_f32_e32 v75, v73, v75
	v_sub_f32_e32 v73, v73, v78
	v_add_f32_e32 v75, v71, v75
	v_add_f32_e32 v71, v71, v73
	v_add_f32_e32 v73, v77, v71
	v_rcp_f32_e32 v78, v73
	v_add_f32_e32 v76, v74, v75
	v_sub_f32_e32 v74, v74, v76
	v_add_f32_e32 v74, v75, v74
	v_sub_f32_e32 v75, v77, v73
	v_add_f32_e32 v71, v71, v75
	v_mul_f32_e32 v75, v76, v78
	v_mul_f32_e32 v77, v73, v75
	v_fma_f32 v79, v75, v73, -v77
	v_fmac_f32_e32 v79, v75, v71
	v_add_f32_e32 v80, v77, v79
	v_sub_f32_e32 v81, v76, v80
	v_sub_f32_e32 v76, v76, v81
	v_sub_f32_e32 v77, v80, v77
	v_sub_f32_e32 v76, v76, v80
	v_add_f32_e32 v74, v74, v76
	v_sub_f32_e32 v76, v77, v79
	v_add_f32_e32 v74, v76, v74
	v_add_f32_e32 v76, v81, v74
	v_mul_f32_e32 v77, v78, v76
	v_mul_f32_e32 v79, v73, v77
	v_fma_f32 v73, v77, v73, -v79
	v_fmac_f32_e32 v73, v77, v71
	v_sub_f32_e32 v71, v81, v76
	v_add_f32_e32 v71, v74, v71
	v_add_f32_e32 v74, v79, v73
	v_sub_f32_e32 v80, v76, v74
	v_sub_f32_e32 v76, v76, v80
	v_sub_f32_e32 v79, v74, v79
	v_sub_f32_e32 v74, v76, v74
	v_add_f32_e32 v71, v71, v74
	v_sub_f32_e32 v73, v79, v73
	v_cvt_f32_i32_e32 v70, v70
	v_add_f32_e32 v71, v73, v71
	v_add_f32_e32 v73, v75, v77
	v_add_f32_e32 v71, v80, v71
	v_sub_f32_e32 v74, v73, v75
	v_mul_f32_e32 v71, v78, v71
	v_sub_f32_e32 v74, v77, v74
	v_add_f32_e32 v71, v74, v71
	v_mul_f32_e32 v77, 0x3f317218, v70
	v_add_f32_e32 v74, v73, v71
	v_fma_f32 v78, v70, s9, -v77
	v_mul_f32_e32 v75, v74, v74
	v_fmac_f32_e32 v78, 0xb102e308, v70
	v_sub_f32_e32 v70, v74, v73
	v_fmamk_f32 v76, v75, 0x3e9b6dac, v123
	v_sub_f32_e32 v70, v71, v70
	v_add_f32_e32 v71, v77, v78
	v_fmaak_f32 v76, v75, v76, 0x3f2aaada
	v_sub_f32_e32 v73, v71, v77
	v_ldexp_f32 v77, v74, 1
	v_mul_f32_e32 v74, v74, v75
	v_mul_f32_e32 v74, v74, v76
	v_add_f32_e32 v75, v77, v74
	v_sub_f32_e32 v76, v75, v77
	v_ldexp_f32 v70, v70, 1
	v_sub_f32_e32 v74, v74, v76
	v_add_f32_e32 v70, v70, v74
	v_add_f32_e32 v74, v75, v70
	v_sub_f32_e32 v75, v74, v75
	v_sub_f32_e32 v70, v70, v75
	v_add_f32_e32 v75, v71, v74
	v_sub_f32_e32 v76, v75, v71
	v_sub_f32_e32 v77, v75, v76
	v_sub_f32_e32 v73, v78, v73
	v_sub_f32_e32 v71, v71, v77
	v_sub_f32_e32 v74, v74, v76
	v_add_f32_e32 v71, v74, v71
	v_add_f32_e32 v74, v73, v70
	v_sub_f32_e32 v76, v74, v73
	v_sub_f32_e32 v77, v74, v76
	v_sub_f32_e32 v73, v73, v77
	v_sub_f32_e32 v70, v70, v76
	v_add_f32_e32 v71, v74, v71
	v_add_f32_e32 v70, v70, v73
	v_add_f32_e32 v73, v75, v71
	v_sub_f32_e32 v74, v73, v75
	v_sub_f32_e32 v71, v71, v74
	v_add_f32_e32 v70, v70, v71
	v_add_f32_e32 v70, v73, v70
	v_cmp_neq_f32_e32 vcc, s3, v72
	v_mul_f32_e64 v71, |v67|, s4
	v_rndne_f32_e32 v73, v71
	v_cndmask_b32_e32 v70, v120, v70, vcc
	v_cmp_lt_f32_e64 vcc, |v72|, s10
	s_nop 1
	v_cndmask_b32_e32 v70, v70, v72, vcc
	v_fma_f32 v72, |v67|, s4, -v71
	v_fma_f32 v72, |v67|, s5, v72
	v_sub_f32_e32 v71, v71, v73
	v_add_f32_e32 v71, v71, v72
	v_exp_f32_e32 v71, v71
	v_cvt_i32_f32_e32 v72, v73
	v_sub_f32_e32 v69, v69, v70
	v_cmp_ngt_f32_e64 vcc, |v67|, s6
	v_min_f32_e32 v73, 0, v67
	v_ldexp_f32 v70, v71, v72
	v_cndmask_b32_e32 v70, 0, v70, vcc
	v_cmp_nlt_f32_e64 vcc, |v67|, s7
	v_add_f32_e32 v69, v66, v69
	s_nop 0
	v_cndmask_b32_e32 v67, v120, v70, vcc
	v_add_f32_e32 v72, 1.0, v67
	v_add_f32_e32 v70, -1.0, v72
	v_sub_f32_e32 v71, v70, v72
	v_add_f32_e32 v71, 1.0, v71
	v_sub_f32_e32 v70, v67, v70
	v_add_f32_e32 v74, v70, v71
	v_frexp_mant_f32_e32 v75, v72
	v_cvt_f64_f32_e32 v[70:71], v72
	v_frexp_exp_i32_f64_e32 v70, v[70:71]
	v_cmp_gt_f32_e32 vcc, s8, v75
	s_nop 1
	v_subbrev_co_u32_e32 v70, vcc, 0, v70, vcc
	v_sub_u32_e32 v71, 0, v70
	v_ldexp_f32 v72, v72, v71
	v_ldexp_f32 v71, v74, v71
	v_add_f32_e32 v74, -1.0, v72
	v_add_f32_e32 v77, 1.0, v72
	v_add_f32_e32 v75, 1.0, v74
	v_add_f32_e32 v78, -1.0, v77
	v_sub_f32_e32 v75, v72, v75
	v_sub_f32_e32 v72, v72, v78
	v_add_f32_e32 v75, v71, v75
	v_add_f32_e32 v71, v71, v72
	v_add_f32_e32 v72, v77, v71
	v_rcp_f32_e32 v78, v72
	v_add_f32_e32 v76, v74, v75
	v_sub_f32_e32 v74, v74, v76
	v_add_f32_e32 v74, v75, v74
	v_sub_f32_e32 v75, v77, v72
	v_add_f32_e32 v71, v71, v75
	v_mul_f32_e32 v75, v76, v78
	v_mul_f32_e32 v77, v72, v75
	v_fma_f32 v79, v75, v72, -v77
	v_fmac_f32_e32 v79, v75, v71
	v_add_f32_e32 v80, v77, v79
	v_sub_f32_e32 v81, v76, v80
	v_sub_f32_e32 v76, v76, v81
	v_sub_f32_e32 v77, v80, v77
	v_sub_f32_e32 v76, v76, v80
	v_add_f32_e32 v74, v74, v76
	v_sub_f32_e32 v76, v77, v79
	v_add_f32_e32 v74, v76, v74
	v_add_f32_e32 v76, v81, v74
	v_mul_f32_e32 v77, v78, v76
	v_mul_f32_e32 v79, v72, v77
	v_fma_f32 v72, v77, v72, -v79
	v_fmac_f32_e32 v72, v77, v71
	v_sub_f32_e32 v71, v81, v76
	v_add_f32_e32 v71, v74, v71
	v_add_f32_e32 v74, v79, v72
	v_sub_f32_e32 v80, v76, v74
	v_sub_f32_e32 v76, v76, v80
	v_sub_f32_e32 v79, v74, v79
	v_sub_f32_e32 v74, v76, v74
	v_add_f32_e32 v71, v71, v74
	v_sub_f32_e32 v72, v79, v72
	v_cvt_f32_i32_e32 v70, v70
	v_add_f32_e32 v71, v72, v71
	v_add_f32_e32 v72, v75, v77
	v_add_f32_e32 v71, v80, v71
	v_sub_f32_e32 v74, v72, v75
	v_mul_f32_e32 v71, v78, v71
	v_sub_f32_e32 v74, v77, v74
	v_add_f32_e32 v71, v74, v71
	v_mul_f32_e32 v76, 0x3f317218, v70
	v_add_f32_e32 v74, v72, v71
	v_fma_f32 v77, v70, s9, -v76
	v_mul_f32_e32 v75, v74, v74
	v_fmac_f32_e32 v77, 0xb102e308, v70
	v_sub_f32_e32 v70, v74, v72
	v_fmac_f32_e32 v123, 0x3e9b6dac, v75
	v_sub_f32_e32 v70, v71, v70
	v_add_f32_e32 v71, v76, v77
	v_fmac_f32_e32 v122, v75, v123
	v_sub_f32_e32 v72, v71, v76
	v_ldexp_f32 v76, v74, 1
	v_mul_f32_e32 v74, v74, v75
	v_mul_f32_e32 v74, v74, v122
	v_add_f32_e32 v75, v76, v74
	v_sub_f32_e32 v76, v75, v76
	v_ldexp_f32 v70, v70, 1
	v_sub_f32_e32 v74, v74, v76
	v_add_f32_e32 v70, v70, v74
	v_add_f32_e32 v74, v75, v70
	v_sub_f32_e32 v75, v74, v75
	v_sub_f32_e32 v70, v70, v75
	v_add_f32_e32 v75, v71, v74
	v_sub_f32_e32 v76, v75, v71
	v_sub_f32_e32 v72, v77, v72
	v_sub_f32_e32 v77, v75, v76
	v_sub_f32_e32 v71, v71, v77
	v_sub_f32_e32 v74, v74, v76
	v_add_f32_e32 v71, v74, v71
	v_add_f32_e32 v74, v72, v70
	v_sub_f32_e32 v76, v74, v72
	v_sub_f32_e32 v77, v74, v76
	v_sub_f32_e32 v72, v72, v77
	v_sub_f32_e32 v70, v70, v76
	v_add_f32_e32 v71, v74, v71
	v_add_f32_e32 v70, v70, v72
	v_add_f32_e32 v72, v75, v71
	v_sub_f32_e32 v74, v72, v75
	v_sub_f32_e32 v71, v71, v74
	v_add_f32_e32 v70, v70, v71
	v_add_f32_e32 v70, v72, v70
	v_cmp_neq_f32_e32 vcc, s3, v67
	v_and_b32_e32 v79, 63, v0
	s_nop 0
	v_cndmask_b32_e32 v70, v120, v70, vcc
	v_cmp_lt_f32_e64 vcc, |v67|, s10
	s_nop 1
	v_cndmask_b32_e32 v67, v70, v67, vcc
	v_sub_f32_e32 v67, v73, v67
	v_mbcnt_hi_u32_b32 v70, -1, v1
	v_add_f32_e32 v71, v69, v67
	v_and_b32_e32 v75, 64, v70
	v_add_u32_e32 v67, -1, v70
	v_cmp_lt_i32_e32 vcc, v67, v75
	s_nop 1
	v_cndmask_b32_e32 v67, v67, v70, vcc
	v_lshlrev_b32_e32 v67, 2, v67
	ds_bpermute_b32 v72, v67, v71
	v_cmp_eq_u32_e32 vcc, 0, v79
	s_waitcnt lgkmcnt(0)
	v_add_f32_e32 v72, v71, v72
	v_cndmask_b32_e32 v73, v72, v71, vcc
	v_add_u32_e32 v72, -2, v70
	v_cmp_lt_i32_e64 s[10:11], v72, v75
	s_nop 1
	v_cndmask_b32_e64 v72, v72, v70, s[10:11]
	v_lshlrev_b32_e32 v72, 2, v72
	ds_bpermute_b32 v74, v72, v73
	v_cmp_gt_u32_e64 s[10:11], 2, v79
	s_waitcnt lgkmcnt(0)
	v_add_f32_e32 v74, v73, v74
	v_cndmask_b32_e64 v74, v74, v73, s[10:11]
	v_add_u32_e32 v73, -4, v70
	v_cmp_lt_i32_e64 s[12:13], v73, v75
	s_nop 1
	v_cndmask_b32_e64 v73, v73, v70, s[12:13]
	v_lshlrev_b32_e32 v73, 2, v73
	ds_bpermute_b32 v76, v73, v74
	v_cmp_gt_u32_e64 s[12:13], 4, v79
	s_waitcnt lgkmcnt(0)
	v_add_f32_e32 v76, v74, v76
	v_cndmask_b32_e64 v76, v76, v74, s[12:13]
	v_add_u32_e32 v74, -8, v70
	v_cmp_lt_i32_e64 s[14:15], v74, v75
	s_nop 1
	v_cndmask_b32_e64 v74, v74, v70, s[14:15]
	v_lshlrev_b32_e32 v74, 2, v74
	ds_bpermute_b32 v77, v74, v76
	v_cmp_gt_u32_e64 s[14:15], 8, v79
	s_waitcnt lgkmcnt(0)
	v_add_f32_e32 v77, v76, v77
	v_cndmask_b32_e64 v76, v77, v76, s[14:15]
	v_add_u32_e32 v77, -16, v70
	v_cmp_lt_i32_e64 s[16:17], v77, v75
	s_nop 1
	v_cndmask_b32_e64 v77, v77, v70, s[16:17]
	v_lshlrev_b32_e32 v77, 2, v77
	ds_bpermute_b32 v78, v77, v76
	v_cmp_gt_u32_e64 s[16:17], 16, v79
	s_waitcnt lgkmcnt(0)
	v_add_f32_e32 v78, v76, v78
	v_cndmask_b32_e64 v80, v78, v76, s[16:17]
	v_subrev_u32_e32 v76, 32, v70
	v_cmp_lt_i32_e64 s[18:19], v76, v75
	s_nop 1
	v_cndmask_b32_e64 v70, v76, v70, s[18:19]
	v_lshlrev_b32_e32 v78, 2, v70
	ds_bpermute_b32 v70, v78, v80
	v_cmp_eq_u32_e64 s[18:19], 63, v79
	s_waitcnt lgkmcnt(0)
	v_add_f32_e32 v81, v80, v70
	v_lshrrev_b32_e32 v70, 6, v0
	v_lshl_add_u32 v75, v70, 2, 0
	s_and_saveexec_b64 s[20:21], s[18:19]
	v_add_u32_e32 v76, 0x21c00, v75
	ds_write_b32 v76, v81
	s_or_b64 exec, exec, s[20:21]
	v_cmp_lt_u32_e64 s[20:21], 63, v0
	v_mov_b32_e32 v86, 0
	v_add_u32_e32 v76, -1, v70
	s_waitcnt lgkmcnt(0)
	s_barrier
	s_and_saveexec_b64 s[42:43], s[20:21]
	s_cbranch_execz .LBB0_602
	v_cmp_lt_u32_e64 s[22:23], 6, v76
	v_mov_b32_e32 v86, 0
	s_and_saveexec_b64 s[44:45], s[22:23]
	s_cbranch_execz .LBB0_597
	s_mov_b32 s0, 0
	s_add_i32 s1, 0, 0x21c00
	s_mov_b64 s[22:23], 0
	v_mov_b32_e32 v86, 0
